# conv phase: second batch of conv operand loads and the decay-projection / v-row loads issued up front with the first batch (copied into place later); on top of write-through XA stores
# speedup vs baseline: 1.0009x; 1.0009x over previous
.LBB0_385:
	s_or_b64 exec, exec, s[6:7]
	v_lshlrev_b32_e32 v76, 1, v18
	v_mov_b32_e32 v77, 0
	v_lshl_add_u64 v[80:81], s[4:5], 0, v[76:77]
	v_lshl_add_u64 v[114:115], s[58:59], 0, v[76:77]
	s_mov_b64 s[4:5], 0x6c00000
	v_lshl_add_u64 v[82:83], v[114:115], 0, s[4:5]
	v_lshlrev_b64 v[20:21], 10, v[78:79]
	v_or_b32_e32 v116, 1, v78
	v_lshl_add_u64 v[22:23], v[80:81], 0, v[20:21]
	v_lshl_add_u64 v[20:21], v[82:83], 0, v[20:21]
	v_ashrrev_i32_e32 v117, 31, v116
	global_load_dwordx4 v[98:101], v[22:23], off
	global_load_dwordx4 v[102:105], v[20:21], off
	v_lshlrev_b64 v[20:21], 10, v[116:117]
	v_or_b32_e32 v86, 2, v78
	v_lshl_add_u64 v[22:23], v[80:81], 0, v[20:21]
	v_lshl_add_u64 v[20:21], v[82:83], 0, v[20:21]
	v_ashrrev_i32_e32 v87, 31, v86
	global_load_dwordx4 v[106:109], v[22:23], off
	global_load_dwordx4 v[110:113], v[20:21], off
	v_lshlrev_b64 v[20:21], 10, v[86:87]
	v_or_b32_e32 v84, 3, v78
	v_lshl_add_u64 v[22:23], v[80:81], 0, v[20:21]
	v_lshl_add_u64 v[20:21], v[82:83], 0, v[20:21]
	v_ashrrev_i32_e32 v85, 31, v84
	global_load_dwordx4 v[50:53], v[22:23], off
	global_load_dwordx4 v[54:57], v[20:21], off
	v_lshlrev_b64 v[20:21], 10, v[84:85]
	v_lshl_add_u64 v[22:23], v[80:81], 0, v[20:21]
	v_lshl_add_u64 v[20:21], v[82:83], 0, v[20:21]
	global_load_dwordx4 v[42:45], v[22:23], off
	global_load_dwordx4 v[46:49], v[20:21], off
	v_lshlrev_b32_e32 v26, 2, v18
	v_mov_b32_e32 v27, v77
	v_lshl_add_u64 v[28:29], s[38:39], 0, v[26:27]
	s_movk_i32 s1, 0x1000
	global_load_dwordx4 v[18:21], v26, s[38:39] offset:2064
	global_load_dwordx4 v[30:33], v26, s[38:39] offset:2048
	global_load_dwordx4 v[22:25], v26, s[38:39] offset:16
	global_load_dwordx4 v[34:37], v26, s[38:39]
	v_add_co_u32_e32 v26, vcc, s1, v28
	s_mov_b64 s[4:5], 0x1000
	s_nop 0
	v_addc_co_u32_e32 v27, vcc, 0, v29, vcc
	global_load_dwordx4 v[38:41], v[26:27], off
	v_lshl_add_u64 v[26:27], v[28:29], 0, s[4:5]
	global_load_dwordx4 v[26:29], v[26:27], off offset:16
	v_or_b32_e32 v184, 5, v78
	v_ashrrev_i32_e32 v185, 31, v184
	v_lshlrev_b64 v[184:185], 10, v[184:185]
	v_or_b32_e32 v186, 4, v78
	v_ashrrev_i32_e32 v187, 31, v186
	v_lshlrev_b64 v[186:187], 10, v[186:187]
	v_or_b32_e32 v188, 7, v78
	v_ashrrev_i32_e32 v189, 31, v188
	v_lshlrev_b64 v[188:189], 10, v[188:189]
	v_or_b32_e32 v190, 6, v78
	v_ashrrev_i32_e32 v191, 31, v190
	v_lshlrev_b64 v[190:191], 10, v[190:191]
	v_lshl_add_u64 v[192:193], v[82:83], 0, v[184:185]
	global_load_dwordx4 v[152:155], v[192:193], off
	v_lshl_add_u64 v[192:193], v[82:83], 0, v[186:187]
	global_load_dwordx4 v[156:159], v[192:193], off
	v_lshl_add_u64 v[192:193], v[80:81], 0, v[186:187]
	global_load_dwordx4 v[160:163], v[192:193], off
	v_lshl_add_u64 v[192:193], v[80:81], 0, v[184:185]
	global_load_dwordx4 v[164:167], v[192:193], off
	v_lshl_add_u64 v[192:193], v[82:83], 0, v[188:189]
	global_load_dwordx4 v[168:171], v[192:193], off
	v_lshl_add_u64 v[192:193], v[80:81], 0, v[188:189]
	global_load_dwordx4 v[172:175], v[192:193], off
	v_lshl_add_u64 v[192:193], v[82:83], 0, v[190:191]
	global_load_dwordx4 v[176:179], v[192:193], off
	v_lshl_add_u64 v[192:193], v[80:81], 0, v[190:191]
	global_load_dwordx4 v[180:183], v[192:193], off
	v_and_b32_e32 v184, 0xff, v0
	v_lshlrev_b32_e32 v184, 2, v184
	v_add_u32_e32 v185, 0x1000, v184
	v_add_u32_e32 v186, 0x2000, v184
	v_add_u32_e32 v187, 0x3000, v184
	global_load_dword v194, v184, s[40:41]
	global_load_dword v195, v184, s[40:41] offset:1024
	global_load_dword v196, v184, s[40:41] offset:2048
	global_load_dword v197, v184, s[40:41] offset:3072
	global_load_dword v198, v185, s[40:41]
	global_load_dword v199, v185, s[40:41] offset:1024
	global_load_dword v200, v185, s[40:41] offset:2048
	global_load_dword v201, v185, s[40:41] offset:3072
	global_load_dword v202, v186, s[40:41]
	global_load_dword v203, v186, s[40:41] offset:1024
	global_load_dword v204, v186, s[40:41] offset:2048
	global_load_dword v205, v186, s[40:41] offset:3072
	global_load_dword v206, v187, s[40:41]
	global_load_dword v207, v187, s[40:41] offset:1024
	global_load_dword v208, v187, s[40:41] offset:2048
	global_load_dword v209, v187, s[40:41] offset:3072
	global_load_dword v210, v184, s[42:43]
	v_lshrrev_b32_e32 v188, 6, v0
	v_or_b32_e32 v188, s0, v188
	v_lshlrev_b32_e32 v189, 4, v1
	s_movk_i32 s98, 0xc00
	v_mul_lo_u32 v188, v188, s98
	v_add_u32_e32 v188, v188, v189
	global_load_dwordx4 v[212:215], v188, s[2:3] offset:1024
	v_add_u32_e32 v190, 0x6000, v188
	global_load_dwordx4 v[216:219], v190, s[2:3] offset:1024
	v_add_u32_e32 v190, 0xc000, v188
	global_load_dwordx4 v[220:223], v190, s[2:3] offset:1024
	v_add_u32_e32 v190, 0x12000, v188
	global_load_dwordx4 v[224:227], v190, s[2:3] offset:1024
	v_add_u32_e32 v190, 0x18000, v188
	global_load_dwordx4 v[228:231], v190, s[2:3] offset:1024
	v_add_u32_e32 v190, 0x1e000, v188
	global_load_dwordx4 v[232:235], v190, s[2:3] offset:1024
	v_add_u32_e32 v190, 0x24000, v188
	global_load_dwordx4 v[236:239], v190, s[2:3] offset:1024
	v_add_u32_e32 v190, 0x2a000, v188
	global_load_dwordx4 v[240:243], v190, s[2:3] offset:1024
	s_mov_b64 s[4:5], 0x4c00000
	s_waitcnt vmcnt(47)
	v_lshlrev_b32_e32 v122, 16, v58
	v_and_b32_e32 v123, 0xffff0000, v58
	v_lshlrev_b32_e32 v126, 16, v59
	v_and_b32_e32 v127, 0xffff0000, v59
	v_lshlrev_b32_e32 v132, 16, v60
	v_and_b32_e32 v133, 0xffff0000, v60
	v_lshlrev_b32_e32 v136, 16, v61
	v_and_b32_e32 v137, 0xffff0000, v61
	v_lshlrev_b64 v[60:61], 11, v[78:79]
	v_lshl_add_u64 v[58:59], v[114:115], 0, s[4:5]
	v_lshlrev_b32_e32 v120, 16, v62
	v_and_b32_e32 v121, 0xffff0000, v62
	v_lshlrev_b32_e32 v62, 16, v63
	v_and_b32_e32 v63, 0xffff0000, v63
	v_lshlrev_b32_e32 v130, 16, v64
	v_and_b32_e32 v131, 0xffff0000, v64
	v_lshlrev_b32_e32 v64, 16, v65
	v_and_b32_e32 v65, 0xffff0000, v65
	v_lshl_add_u64 v[114:115], v[58:59], 0, v[60:61]
	s_waitcnt vmcnt(46)
	v_lshlrev_b32_e32 v124, 16, v98
	v_and_b32_e32 v125, 0xffff0000, v98
	v_lshlrev_b32_e32 v128, 16, v99
	v_and_b32_e32 v129, 0xffff0000, v99
	v_lshlrev_b32_e32 v134, 16, v100
	v_and_b32_e32 v135, 0xffff0000, v100
	v_lshlrev_b32_e32 v138, 16, v101
	v_and_b32_e32 v139, 0xffff0000, v101
	s_waitcnt vmcnt(45)
	v_lshlrev_b32_e32 v118, 16, v102
	v_and_b32_e32 v119, 0xffff0000, v102
	v_lshlrev_b32_e32 v102, 16, v103
	v_and_b32_e32 v103, 0xffff0000, v103
	v_lshlrev_b32_e32 v98, 16, v104
	v_and_b32_e32 v99, 0xffff0000, v104
	v_lshlrev_b32_e32 v104, 16, v105
	v_and_b32_e32 v105, 0xffff0000, v105
	s_waitcnt vmcnt(43)
	v_lshlrev_b32_e32 v100, 16, v110
	v_and_b32_e32 v101, 0xffff0000, v110
	v_lshlrev_b32_e32 v110, 16, v111
	v_and_b32_e32 v111, 0xffff0000, v111
	v_lshlrev_b32_e32 v140, 16, v106
	v_and_b32_e32 v141, 0xffff0000, v106
	s_waitcnt vmcnt(42)
	v_lshlrev_b32_e32 v106, 16, v50
	s_waitcnt vmcnt(38)
	v_pk_mul_f32 v[144:145], v[18:19], v[132:133]
	s_waitcnt vmcnt(37)
	v_pk_mul_f32 v[60:61], v[30:31], v[122:123]
	v_pk_mul_f32 v[142:143], v[32:33], v[126:127]
	v_pk_mul_f32 v[146:147], v[20:21], v[136:137]
	s_waitcnt vmcnt(35)
	v_pk_fma_f32 v[60:61], v[34:35], v[120:121], v[60:61]
	v_pk_fma_f32 v[62:63], v[36:37], v[62:63], v[142:143]
	v_pk_fma_f32 v[120:121], v[22:23], v[130:131], v[144:145]
	v_pk_fma_f32 v[64:65], v[24:25], v[64:65], v[146:147]
	s_waitcnt vmcnt(34)
	v_pk_fma_f32 v[60:61], v[38:39], v[124:125], v[60:61]
	v_pk_fma_f32 v[62:63], v[40:41], v[128:129], v[62:63]
	s_waitcnt vmcnt(33)
	v_pk_fma_f32 v[120:121], v[26:27], v[134:135], v[120:121]
	v_pk_fma_f32 v[64:65], v[28:29], v[138:139], v[64:65]
	v_pk_mul_f32 v[60:61], v[60:61], v[118:119]
	v_pk_mul_f32 v[62:63], v[62:63], v[102:103]
	v_pk_mul_f32 v[98:99], v[120:121], v[98:99]
	v_pk_mul_f32 v[64:65], v[64:65], v[104:105]
	v_pk_mul_f32 v[150:151], v[32:33], v[128:129]
	v_cvt_pk_bf16_f32 v60, v60, v61
	v_cvt_pk_bf16_f32 v61, v62, v63
	v_cvt_pk_bf16_f32 v62, v98, v99
	v_cvt_pk_bf16_f32 v63, v64, v65
	global_store_dwordx4 v[114:115], v[60:63], off
	v_pk_mul_f32 v[64:65], v[18:19], v[134:135]
	v_pk_mul_f32 v[148:149], v[30:31], v[124:125]
	v_pk_fma_f32 v[60:61], v[36:37], v[126:127], v[150:151]
	v_lshlrev_b32_e32 v62, 16, v107
	v_and_b32_e32 v63, 0xffff0000, v107
	v_pk_fma_f32 v[60:61], v[40:41], v[62:63], v[60:61]
	v_pk_fma_f32 v[64:65], v[22:23], v[132:133], v[64:65]
	v_pk_mul_f32 v[60:61], v[60:61], v[110:111]
	v_lshlrev_b32_e32 v102, 16, v108
	v_and_b32_e32 v103, 0xffff0000, v108
	v_pk_fma_f32 v[122:123], v[34:35], v[122:123], v[148:149]
	v_cvt_pk_bf16_f32 v99, v60, v61
	v_lshlrev_b32_e32 v60, 16, v112
	v_and_b32_e32 v61, 0xffff0000, v112
	v_pk_fma_f32 v[64:65], v[26:27], v[102:103], v[64:65]
	v_pk_fma_f32 v[122:123], v[38:39], v[140:141], v[122:123]
	v_pk_mul_f32 v[60:61], v[64:65], v[60:61]
	v_pk_mul_f32 v[64:65], v[20:21], v[138:139]
	v_pk_mul_f32 v[100:101], v[122:123], v[100:101]
	v_pk_fma_f32 v[64:65], v[24:25], v[136:137], v[64:65]
	v_lshlrev_b32_e32 v104, 16, v109
	v_and_b32_e32 v105, 0xffff0000, v109
	v_cvt_pk_bf16_f32 v98, v100, v101
	v_cvt_pk_bf16_f32 v100, v60, v61
	v_lshlrev_b32_e32 v60, 16, v113
	v_and_b32_e32 v61, 0xffff0000, v113
	v_pk_fma_f32 v[64:65], v[28:29], v[104:105], v[64:65]
	v_and_b32_e32 v107, 0xffff0000, v50
	v_pk_mul_f32 v[60:61], v[64:65], v[60:61]
	v_pk_mul_f32 v[64:65], v[30:31], v[140:141]
	v_cvt_pk_bf16_f32 v101, v60, v61
	v_lshlrev_b64 v[60:61], 11, v[116:117]
	v_lshl_add_u64 v[60:61], v[58:59], 0, v[60:61]
	v_pk_fma_f32 v[64:65], v[34:35], v[124:125], v[64:65]
	global_store_dwordx4 v[60:61], v[98:101], off
	v_lshlrev_b32_e32 v60, 16, v54
	v_and_b32_e32 v61, 0xffff0000, v54
	v_pk_fma_f32 v[64:65], v[38:39], v[106:107], v[64:65]
	v_lshlrev_b32_e32 v54, 16, v55
	v_pk_mul_f32 v[60:61], v[64:65], v[60:61]
	v_lshlrev_b32_e32 v64, 16, v51
	v_cvt_pk_bf16_f32 v50, v60, v61
	v_pk_mul_f32 v[60:61], v[32:33], v[62:63]
	v_and_b32_e32 v65, 0xffff0000, v51
	v_pk_fma_f32 v[60:61], v[36:37], v[128:129], v[60:61]
	v_and_b32_e32 v55, 0xffff0000, v55
	v_pk_fma_f32 v[60:61], v[40:41], v[64:65], v[60:61]
	v_lshlrev_b32_e32 v108, 16, v52
	v_pk_mul_f32 v[54:55], v[60:61], v[54:55]
	v_pk_mul_f32 v[60:61], v[18:19], v[102:103]
	v_and_b32_e32 v109, 0xffff0000, v52
	v_pk_fma_f32 v[60:61], v[22:23], v[134:135], v[60:61]
	v_cvt_pk_bf16_f32 v51, v54, v55
	v_lshlrev_b32_e32 v54, 16, v56
	v_and_b32_e32 v55, 0xffff0000, v56
	v_pk_fma_f32 v[60:61], v[26:27], v[108:109], v[60:61]
	v_lshlrev_b32_e32 v110, 16, v53
	v_pk_mul_f32 v[54:55], v[60:61], v[54:55]
	v_and_b32_e32 v111, 0xffff0000, v53
	v_cvt_pk_bf16_f32 v52, v54, v55
	v_lshlrev_b32_e32 v54, 16, v57
	v_and_b32_e32 v55, 0xffff0000, v57
	v_pk_mul_f32 v[56:57], v[20:21], v[104:105]
	v_lshlrev_b32_e32 v112, 16, v42
	v_pk_fma_f32 v[56:57], v[24:25], v[138:139], v[56:57]
	v_and_b32_e32 v113, 0xffff0000, v42
	v_pk_fma_f32 v[56:57], v[28:29], v[110:111], v[56:57]
	v_lshlrev_b32_e32 v114, 16, v43
	v_pk_mul_f32 v[54:55], v[56:57], v[54:55]
	v_and_b32_e32 v115, 0xffff0000, v43
	v_cvt_pk_bf16_f32 v53, v54, v55
	v_lshlrev_b64 v[54:55], 11, v[86:87]
	v_lshl_add_u64 v[54:55], v[58:59], 0, v[54:55]
	global_store_dwordx4 v[54:55], v[50:53], off
	v_or_b32_e32 v116, 4, v78
	v_ashrrev_i32_e32 v117, 31, v116
	v_pk_mul_f32 v[52:53], v[30:31], v[106:107]
	v_lshlrev_b32_e32 v50, 16, v46
	v_pk_fma_f32 v[52:53], v[34:35], v[140:141], v[52:53]
	v_and_b32_e32 v51, 0xffff0000, v46
	v_pk_fma_f32 v[52:53], v[38:39], v[112:113], v[52:53]
	v_lshlrev_b32_e32 v46, 16, v47
	v_pk_mul_f32 v[50:51], v[52:53], v[50:51]
	v_and_b32_e32 v47, 0xffff0000, v47
	v_cvt_pk_bf16_f32 v42, v50, v51
	v_pk_mul_f32 v[50:51], v[32:33], v[64:65]
	v_or_b32_e32 v118, 5, v78
	v_pk_fma_f32 v[50:51], v[36:37], v[62:63], v[50:51]
	v_ashrrev_i32_e32 v119, 31, v118
	v_pk_fma_f32 v[50:51], v[40:41], v[114:115], v[50:51]
	v_lshlrev_b64 v[54:55], 10, v[118:119]
	v_pk_mul_f32 v[46:47], v[50:51], v[46:47]
	v_pk_mul_f32 v[50:51], v[18:19], v[108:109]
	v_cvt_pk_bf16_f32 v43, v46, v47
	v_pk_fma_f32 v[50:51], v[22:23], v[102:103], v[50:51]
	v_lshlrev_b32_e32 v102, 16, v44
	v_and_b32_e32 v103, 0xffff0000, v44
	v_lshlrev_b32_e32 v46, 16, v48
	v_and_b32_e32 v47, 0xffff0000, v48
	v_pk_fma_f32 v[50:51], v[26:27], v[102:103], v[50:51]
	v_or_b32_e32 v120, 7, v78
	v_pk_mul_f32 v[46:47], v[50:51], v[46:47]
	v_lshl_add_u64 v[50:51], v[82:83], 0, v[54:55]
	v_cvt_pk_bf16_f32 v44, v46, v47
	v_lshlrev_b32_e32 v46, 16, v49
	v_and_b32_e32 v47, 0xffff0000, v49
	v_pk_mul_f32 v[48:49], v[20:21], v[110:111]
	v_lshl_add_u64 v[54:55], v[80:81], 0, v[54:55]
	v_pk_fma_f32 v[48:49], v[24:25], v[104:105], v[48:49]
	v_lshlrev_b32_e32 v104, 16, v45
	v_and_b32_e32 v105, 0xffff0000, v45
	v_pk_fma_f32 v[48:49], v[28:29], v[104:105], v[48:49]
	v_or_b32_e32 v122, 6, v78
	v_pk_mul_f32 v[46:47], v[48:49], v[46:47]
	v_ashrrev_i32_e32 v121, 31, v120
	v_cvt_pk_bf16_f32 v45, v46, v47
	v_lshlrev_b64 v[46:47], 11, v[84:85]
	v_lshl_add_u64 v[46:47], v[58:59], 0, v[46:47]
	global_store_dwordx4 v[46:47], v[42:45], off
	v_lshlrev_b64 v[46:47], 10, v[116:117]
	s_waitcnt vmcnt(29)
	v_mov_b32_e32 v50, v152
	v_mov_b32_e32 v51, v153
	v_mov_b32_e32 v52, v154
	v_mov_b32_e32 v53, v155
	v_lshl_add_u64 v[42:43], v[82:83], 0, v[46:47]
	v_lshl_add_u64 v[46:47], v[80:81], 0, v[46:47]
	v_mov_b32_e32 v42, v156
	v_mov_b32_e32 v43, v157
	v_mov_b32_e32 v44, v158
	v_mov_b32_e32 v45, v159
	v_ashrrev_i32_e32 v123, 31, v122
	v_mov_b32_e32 v46, v160
	v_mov_b32_e32 v47, v161
	v_mov_b32_e32 v48, v162
	v_mov_b32_e32 v49, v163
	v_lshlrev_b64 v[60:61], 10, v[120:121]
	v_mov_b32_e32 v54, v164
	v_mov_b32_e32 v55, v165
	v_mov_b32_e32 v56, v166
	v_mov_b32_e32 v57, v167
	v_lshlrev_b64 v[78:79], 10, v[122:123]
	v_lshl_add_u64 v[98:99], v[82:83], 0, v[60:61]
	v_lshl_add_u64 v[100:101], v[80:81], 0, v[60:61]
	v_lshl_add_u64 v[82:83], v[82:83], 0, v[78:79]
	v_mov_b32_e32 v60, v168
	v_mov_b32_e32 v61, v169
	v_mov_b32_e32 v62, v170
	v_mov_b32_e32 v63, v171
	v_mov_b32_e32 v84, v172
	v_mov_b32_e32 v85, v173
	v_mov_b32_e32 v86, v174
	v_mov_b32_e32 v87, v175
	v_lshl_add_u64 v[124:125], v[80:81], 0, v[78:79]
	v_mov_b32_e32 v78, v176
	v_mov_b32_e32 v79, v177
	v_mov_b32_e32 v80, v178
	v_mov_b32_e32 v81, v179
	v_mov_b32_e32 v98, v180
	v_mov_b32_e32 v99, v181
	v_mov_b32_e32 v100, v182
	v_mov_b32_e32 v101, v183
	v_pk_mul_f32 v[124:125], v[30:31], v[112:113]
	s_nop 0
	v_lshlrev_b32_e32 v82, 16, v42
	v_pk_fma_f32 v[106:107], v[34:35], v[106:107], v[124:125]
	s_nop 0
	v_lshlrev_b32_e32 v124, 16, v46
	v_and_b32_e32 v125, 0xffff0000, v46
	v_and_b32_e32 v83, 0xffff0000, v42
	v_pk_fma_f32 v[106:107], v[38:39], v[124:125], v[106:107]
	v_lshlrev_b32_e32 v46, 16, v47
	v_pk_mul_f32 v[82:83], v[106:107], v[82:83]
	v_pk_mul_f32 v[106:107], v[32:33], v[114:115]
	v_and_b32_e32 v47, 0xffff0000, v47
	v_pk_fma_f32 v[64:65], v[36:37], v[64:65], v[106:107]
	v_cvt_pk_bf16_f32 v42, v82, v83
	v_lshlrev_b32_e32 v82, 16, v43
	v_and_b32_e32 v83, 0xffff0000, v43
	v_pk_fma_f32 v[64:65], v[40:41], v[46:47], v[64:65]
	v_lshlrev_b32_e32 v106, 16, v48
	v_pk_mul_f32 v[64:65], v[64:65], v[82:83]
	v_pk_mul_f32 v[82:83], v[18:19], v[102:103]
	v_and_b32_e32 v107, 0xffff0000, v48
	v_pk_fma_f32 v[82:83], v[22:23], v[108:109], v[82:83]
	v_cvt_pk_bf16_f32 v43, v64, v65
	v_lshlrev_b32_e32 v64, 16, v44
	v_and_b32_e32 v65, 0xffff0000, v44
	v_pk_fma_f32 v[82:83], v[26:27], v[106:107], v[82:83]
	v_lshlrev_b32_e32 v48, 16, v49
	v_pk_mul_f32 v[64:65], v[82:83], v[64:65]
	v_pk_mul_f32 v[82:83], v[20:21], v[104:105]
	v_and_b32_e32 v49, 0xffff0000, v49
	v_pk_fma_f32 v[82:83], v[24:25], v[110:111], v[82:83]
	v_cvt_pk_bf16_f32 v44, v64, v65
	v_lshlrev_b32_e32 v64, 16, v45
	v_and_b32_e32 v65, 0xffff0000, v45
	v_pk_fma_f32 v[82:83], v[28:29], v[48:49], v[82:83]
	s_nop 0
	v_pk_mul_f32 v[64:65], v[82:83], v[64:65]
	s_nop 0
	v_lshlrev_b32_e32 v82, 16, v56
	v_cvt_pk_bf16_f32 v45, v64, v65
	v_lshlrev_b64 v[64:65], 11, v[116:117]
	v_lshl_add_u64 v[64:65], v[58:59], 0, v[64:65]
	global_store_dwordx4 v[64:65], v[42:45], off
	v_lshlrev_b32_e32 v64, 16, v54
	v_and_b32_e32 v65, 0xffff0000, v54
	v_pk_mul_f32 v[44:45], v[30:31], v[124:125]
	v_lshlrev_b32_e32 v42, 16, v50
	v_pk_fma_f32 v[44:45], v[34:35], v[112:113], v[44:45]
	v_and_b32_e32 v43, 0xffff0000, v50
	v_pk_fma_f32 v[44:45], v[38:39], v[64:65], v[44:45]
	v_lshlrev_b32_e32 v54, 16, v55
	v_pk_mul_f32 v[42:43], v[44:45], v[42:43]
	v_lshlrev_b32_e32 v44, 16, v51
	v_and_b32_e32 v45, 0xffff0000, v51
	v_pk_mul_f32 v[50:51], v[32:33], v[46:47]
	v_and_b32_e32 v55, 0xffff0000, v55
	v_pk_fma_f32 v[50:51], v[36:37], v[114:115], v[50:51]
	v_and_b32_e32 v83, 0xffff0000, v56
	v_pk_fma_f32 v[50:51], v[40:41], v[54:55], v[50:51]
	v_cvt_pk_bf16_f32 v42, v42, v43
	v_pk_mul_f32 v[44:45], v[50:51], v[44:45]
	v_pk_mul_f32 v[50:51], v[18:19], v[106:107]
	v_cvt_pk_bf16_f32 v43, v44, v45
	v_pk_fma_f32 v[50:51], v[22:23], v[102:103], v[50:51]
	v_lshlrev_b32_e32 v44, 16, v52
	v_and_b32_e32 v45, 0xffff0000, v52
	v_pk_fma_f32 v[50:51], v[26:27], v[82:83], v[50:51]
	v_lshlrev_b32_e32 v56, 16, v57
	v_pk_mul_f32 v[44:45], v[50:51], v[44:45]
	v_lshlrev_b32_e32 v50, 16, v53
	v_and_b32_e32 v51, 0xffff0000, v53
	v_pk_mul_f32 v[52:53], v[20:21], v[48:49]
	v_and_b32_e32 v57, 0xffff0000, v57
	v_pk_fma_f32 v[52:53], v[24:25], v[104:105], v[52:53]
	v_cvt_pk_bf16_f32 v44, v44, v45
	v_pk_fma_f32 v[52:53], v[28:29], v[56:57], v[52:53]
	v_pk_mul_f32 v[46:47], v[36:37], v[46:47]
	v_pk_mul_f32 v[50:51], v[52:53], v[50:51]
	v_pk_fma_f32 v[46:47], v[32:33], v[54:55], v[46:47]
	v_cvt_pk_bf16_f32 v45, v50, v51
	v_lshlrev_b64 v[50:51], 11, v[118:119]
	v_lshl_add_u64 v[50:51], v[58:59], 0, v[50:51]
	global_store_dwordx4 v[50:51], v[42:45], off
	s_nop 0
	v_lshlrev_b32_e32 v50, 16, v98
	v_and_b32_e32 v51, 0xffff0000, v98
	v_pk_mul_f32 v[44:45], v[34:35], v[124:125]
	v_lshlrev_b32_e32 v42, 16, v78
	v_pk_fma_f32 v[44:45], v[30:31], v[64:65], v[44:45]
	v_and_b32_e32 v43, 0xffff0000, v78
	v_pk_fma_f32 v[44:45], v[38:39], v[50:51], v[44:45]
	v_lshlrev_b32_e32 v52, 16, v99
	v_and_b32_e32 v53, 0xffff0000, v99
	v_pk_mul_f32 v[42:43], v[44:45], v[42:43]
	v_lshlrev_b32_e32 v44, 16, v79
	v_and_b32_e32 v45, 0xffff0000, v79
	v_pk_fma_f32 v[46:47], v[40:41], v[52:53], v[46:47]
	v_lshlrev_b32_e32 v78, 16, v100
	v_pk_mul_f32 v[44:45], v[46:47], v[44:45]
	v_pk_mul_f32 v[46:47], v[22:23], v[106:107]
	v_and_b32_e32 v79, 0xffff0000, v100
	v_pk_fma_f32 v[46:47], v[18:19], v[82:83], v[46:47]
	v_cvt_pk_bf16_f32 v42, v42, v43
	v_cvt_pk_bf16_f32 v43, v44, v45
	v_lshlrev_b32_e32 v44, 16, v80
	v_and_b32_e32 v45, 0xffff0000, v80
	v_pk_fma_f32 v[46:47], v[26:27], v[78:79], v[46:47]
	v_pk_mul_f32 v[48:49], v[24:25], v[48:49]
	v_pk_mul_f32 v[44:45], v[46:47], v[44:45]
	v_lshlrev_b32_e32 v46, 16, v81
	v_and_b32_e32 v47, 0xffff0000, v81
	v_pk_fma_f32 v[48:49], v[20:21], v[56:57], v[48:49]
	v_lshlrev_b32_e32 v80, 16, v101
	v_and_b32_e32 v81, 0xffff0000, v101
	v_pk_fma_f32 v[48:49], v[28:29], v[80:81], v[48:49]
	v_cvt_pk_bf16_f32 v44, v44, v45
	v_pk_mul_f32 v[46:47], v[48:49], v[46:47]
	v_pk_mul_f32 v[34:35], v[34:35], v[64:65]
	v_cvt_pk_bf16_f32 v45, v46, v47
	v_lshlrev_b64 v[46:47], 11, v[122:123]
	v_pk_mul_f32 v[36:37], v[36:37], v[54:55]
	v_lshl_add_u64 v[46:47], v[58:59], 0, v[46:47]
	v_pk_fma_f32 v[30:31], v[30:31], v[50:51], v[34:35]
	v_lshlrev_b32_e32 v34, 16, v84
	v_and_b32_e32 v35, 0xffff0000, v84
	v_pk_fma_f32 v[32:33], v[32:33], v[52:53], v[36:37]
	v_lshlrev_b32_e32 v36, 16, v85
	v_and_b32_e32 v37, 0xffff0000, v85
	global_store_dwordx4 v[46:47], v[42:45], off
	v_pk_fma_f32 v[30:31], v[38:39], v[34:35], v[30:31]
	v_lshlrev_b32_e32 v34, 16, v61
	v_lshlrev_b32_e32 v42, 16, v60
	v_and_b32_e32 v43, 0xffff0000, v60
	v_and_b32_e32 v35, 0xffff0000, v61
	v_pk_fma_f32 v[32:33], v[40:41], v[36:37], v[32:33]
	v_pk_mul_f32 v[22:23], v[22:23], v[82:83]
	v_pk_mul_f32 v[30:31], v[30:31], v[42:43]
	v_pk_mul_f32 v[32:33], v[32:33], v[34:35]
	v_pk_fma_f32 v[18:19], v[18:19], v[78:79], v[22:23]
	v_lshlrev_b32_e32 v22, 16, v86
	v_and_b32_e32 v23, 0xffff0000, v86
	v_cvt_pk_bf16_f32 v30, v30, v31
	v_cvt_pk_bf16_f32 v31, v32, v33
	v_lshlrev_b32_e32 v32, 16, v62
	v_and_b32_e32 v33, 0xffff0000, v62
	v_pk_fma_f32 v[18:19], v[26:27], v[22:23], v[18:19]
	v_pk_mul_f32 v[22:23], v[24:25], v[56:57]
	v_pk_mul_f32 v[18:19], v[18:19], v[32:33]
	v_pk_fma_f32 v[20:21], v[20:21], v[80:81], v[22:23]
	v_lshlrev_b32_e32 v22, 16, v87
	v_and_b32_e32 v23, 0xffff0000, v87
	v_cvt_pk_bf16_f32 v32, v18, v19
	v_lshlrev_b32_e32 v18, 16, v63
	v_and_b32_e32 v19, 0xffff0000, v63
	v_pk_fma_f32 v[20:21], v[28:29], v[22:23], v[20:21]
	s_nop 0
	v_pk_mul_f32 v[18:19], v[20:21], v[18:19]
	s_nop 0
	v_cvt_pk_bf16_f32 v33, v18, v19
	v_lshlrev_b64 v[18:19], 11, v[120:121]
	v_lshl_add_u64 v[18:19], v[58:59], 0, v[18:19]
	global_store_dwordx4 v[18:19], v[30:33], off
	v_lshrrev_b32_e32 v78, 6, v0
	v_or_b32_e32 v22, s0, v78
	s_movk_i32 s4, 0xc00
	v_mov_b64_e32 v[18:19], s[2:3]
	v_mad_i64_i32 v[20:21], s[2:3], v22, s4, v[18:19]
	v_lshrrev_b32_e32 v79, 6, v94
	v_lshl_add_u64 v[86:87], v[20:21], 0, v[76:77]
	v_or_b32_e32 v20, s0, v79
	v_mad_i64_i32 v[20:21], s[2:3], v20, s4, v[18:19]
	v_lshrrev_b32_e32 v80, 6, v95
	v_lshl_add_u64 v[98:99], v[20:21], 0, v[76:77]
	v_or_b32_e32 v20, s0, v80
	v_mad_i64_i32 v[20:21], s[2:3], v20, s4, v[18:19]
	v_lshrrev_b32_e32 v81, 6, v96
	v_lshl_add_u64 v[94:95], v[20:21], 0, v[76:77]
	v_or_b32_e32 v20, s0, v81
	v_mad_i64_i32 v[20:21], s[2:3], v20, s4, v[18:19]
	v_lshl_add_u64 v[96:97], v[20:21], 0, v[76:77]
	v_or_b32_e32 v20, 32, v22
	v_mad_i64_i32 v[20:21], s[2:3], v20, s4, v[18:19]
	v_lshl_add_u64 v[100:101], v[20:21], 0, v[76:77]
	v_or_b32_e32 v20, 0xa00, v0
	v_lshrrev_b32_e32 v82, 6, v20
	v_or_b32_e32 v20, s0, v82
	v_mad_i64_i32 v[20:21], s[2:3], v20, s4, v[18:19]
	v_lshl_add_u64 v[102:103], v[20:21], 0, v[76:77]
	v_or_b32_e32 v20, 48, v22
	v_mad_i64_i32 v[20:21], s[2:3], v20, s4, v[18:19]
	v_lshl_add_u64 v[104:105], v[20:21], 0, v[76:77]
	v_or_b32_e32 v20, 0xe00, v0
	v_lshrrev_b32_e32 v83, 6, v20
	v_add_u32_e32 v20, s0, v83
	v_mad_i64_i32 v[18:19], s[2:3], v20, s4, v[18:19]
	v_and_b32_e32 v84, 0xff, v0
	v_lshl_add_u64 v[106:107], v[18:19], 0, v[76:77]
	v_lshlrev_b32_e32 v76, 2, v84
	v_lshl_add_u64 v[18:19], s[40:41], 0, v[76:77]
	v_add_co_u32_e32 v20, vcc, s1, v18
	s_movk_i32 s0, 0x2000
	s_nop 0
	v_addc_co_u32_e32 v21, vcc, 0, v19, vcc
	v_lshlrev_b32_e32 v24, 2, v0
	v_add_co_u32_e32 v22, vcc, s0, v18
	v_or_b32_e32 v25, 0xc00, v24
	s_nop 0
	v_addc_co_u32_e32 v23, vcc, 0, v19, vcc
	s_waitcnt vmcnt(8)
	v_mov_b32_e32 v52, v194
	v_mov_b32_e32 v54, v195
	v_mov_b32_e32 v53, v198
	v_or_b32_e32 v26, 0x1c00, v24
	v_mov_b32_e32 v50, v197
	v_mov_b32_e32 v55, v199
	v_mov_b32_e32 v61, v200
	v_mov_b32_e32 v51, v201
	s_movk_i32 s0, 0x3000
	v_mov_b32_e32 v60, v196
	v_mov_b32_e32 v56, v202
	v_mov_b32_e32 v58, v203
	v_mov_b32_e32 v85, v210
	v_add_co_u32_e32 v18, vcc, s0, v18
	v_or_b32_e32 v20, 0x2c00, v24
	s_nop 0
	v_addc_co_u32_e32 v19, vcc, 0, v19, vcc
	v_mov_b32_e32 v57, v206
	v_mov_b32_e32 v59, v207
	v_mov_b32_e32 v64, v204
	v_mov_b32_e32 v62, v205
	v_mov_b32_e32 v65, v208
	v_or_b32_e32 v108, 0x3c00, v24
	v_mov_b32_e32 v63, v209
	v_mov_b32_e32 v46, v212
	v_mov_b32_e32 v47, v213
	v_mov_b32_e32 v48, v214
	v_mov_b32_e32 v49, v215
	v_mov_b32_e32 v42, v216
	v_mov_b32_e32 v43, v217
	v_mov_b32_e32 v44, v218
	v_mov_b32_e32 v45, v219
	v_mov_b32_e32 v38, v220
	v_mov_b32_e32 v39, v221
	v_mov_b32_e32 v40, v222
	v_mov_b32_e32 v41, v223
	v_mov_b32_e32 v30, v224
	v_mov_b32_e32 v31, v225
	v_mov_b32_e32 v32, v226
	v_mov_b32_e32 v33, v227
	v_mov_b32_e32 v34, v228
	v_mov_b32_e32 v35, v229
	v_mov_b32_e32 v36, v230
	v_mov_b32_e32 v37, v231
	v_mov_b32_e32 v22, v232
	v_mov_b32_e32 v23, v233
	v_mov_b32_e32 v24, v234
	v_mov_b32_e32 v25, v235
	v_mov_b32_e32 v26, v236
	v_mov_b32_e32 v27, v237
	v_mov_b32_e32 v28, v238
	v_mov_b32_e32 v29, v239
	v_mov_b32_e32 v18, v240
	v_mov_b32_e32 v19, v241
	v_mov_b32_e32 v20, v242
	v_mov_b32_e32 v21, v243
	v_readlane_b32 s6, v254, 18
	v_readlane_b32 s7, v254, 19
	v_pk_add_f32 v[68:69], v[68:69], v[70:71]
	v_pk_add_f32 v[70:71], v[72:73], v[74:75]
	s_ashr_i32 s7, s6, 31
	v_pk_add_f32 v[68:69], v[68:69], v[70:71]
	s_add_i32 s0, 0, 0x23000
	v_lshlrev_b32_e32 v70, 2, v67
	s_lshl_b64 s[2:3], s[6:7], 12
	v_add_u32_e32 v71, s0, v70
	s_add_u32 s2, s58, s2
	ds_write_b64 v71, v[68:69]
	s_addc_u32 s3, s59, s3
	v_mov_b32_e32 v71, v77
	v_lshl_add_u64 v[70:71], s[2:3], 0, v[70:71]
	s_mov_b32 s1, 0x200000
	v_add_co_u32_e32 v70, vcc, s1, v70
	s_mov_b32 s1, 0xbd800000
	s_nop 0
	v_addc_co_u32_e32 v71, vcc, 0, v71, vcc
	global_store_dwordx2 v[70:71], v[68:69], off
	v_and_b32_e32 v70, 32, v93
	v_lshl_add_u32 v68, v70, 6, s0
	s_waitcnt lgkmcnt(0)
	s_barrier
	ds_read_b128 v[72:75], v68
	ds_read_b128 v[94:97], v68 offset:16
	ds_read_b128 v[98:101], v68 offset:32
	ds_read_b128 v[102:105], v68 offset:48
	v_or_b32_e32 v86, 2, v70
	s_waitcnt lgkmcnt(3)
	v_mov_b32_e32 v68, v72
	s_waitcnt lgkmcnt(2)
	v_mov_b32_e32 v69, v94
	v_mov_b32_e32 v94, v73
	v_or_b32_e32 v106, 29, v70
	v_or_b32_e32 v93, 31, v93
	s_waitcnt vmcnt(21)
	v_pk_mul_f32 v[72:73], v[54:55], v[94:95]
	s_nop 0
	v_pk_fma_f32 v[68:69], v[52:53], v[68:69], v[72:73]
	v_mov_b32_e32 v72, v74
	v_mov_b32_e32 v73, v96
	s_waitcnt vmcnt(18)
	v_pk_fma_f32 v[68:69], v[60:61], v[72:73], v[68:69]
	v_mov_b32_e32 v96, v75
	v_pk_fma_f32 v[68:69], v[50:51], v[96:97], v[68:69]
	s_waitcnt vmcnt(15)
	v_add_f32_e32 v68, v85, v68
	v_add_f32_e32 v71, v68, v69
	s_waitcnt lgkmcnt(0)
	v_mov_b32_e32 v69, v102
	v_mov_b32_e32 v102, v99
	v_mov_b32_e32 v68, v98
	s_waitcnt vmcnt(13)
	v_pk_mul_f32 v[72:73], v[58:59], v[102:103]
	s_nop 0
	v_pk_fma_f32 v[68:69], v[56:57], v[68:69], v[72:73]
	v_mov_b32_e32 v72, v100
	v_mov_b32_e32 v73, v104
	s_waitcnt vmcnt(10)
	v_pk_fma_f32 v[68:69], v[64:65], v[72:73], v[68:69]
	v_mov_b32_e32 v104, v101
	s_waitcnt vmcnt(9)
	v_pk_fma_f32 v[68:69], v[62:63], v[104:105], v[68:69]
	s_nop 0
	v_add_f32_e32 v68, v71, v68
	v_add_f32_e32 v68, v68, v69
	v_max_f32_e32 v68, 0xc2a00000, v68
	v_mul_f32_e32 v68, 0xbfb8aa3b, v68
	v_exp_f32_e32 v68, v68
	v_or_b32_e32 v71, 1, v70
	v_add_f32_e32 v68, 1.0, v68
	v_log_f32_e32 v69, v68
	v_add_u32_e32 v68, 0, v76
	v_lshl_add_u32 v76, v71, 6, s0
	ds_read_b128 v[72:75], v76
	ds_read_b128 v[94:97], v76 offset:16
	ds_read_b128 v[98:101], v76 offset:32
	ds_read_b128 v[102:105], v76 offset:48
	v_mul_f32_e32 v69, 0x3f317218, v69
	v_fma_f32 v69, v69, s1, 0
	s_waitcnt lgkmcnt(3)
	v_mov_b32_e32 v76, v72
	s_waitcnt lgkmcnt(2)
	v_mov_b32_e32 v77, v94
	v_mov_b32_e32 v94, v73
	v_pk_mul_f32 v[72:73], v[54:55], v[94:95]
	v_lshl_add_u32 v71, v71, 10, v68
	v_pk_fma_f32 v[72:73], v[52:53], v[76:77], v[72:73]
	v_mov_b32_e32 v76, v74
	v_mov_b32_e32 v77, v96
	v_pk_fma_f32 v[72:73], v[60:61], v[76:77], v[72:73]
	v_mov_b32_e32 v96, v75
	v_pk_fma_f32 v[72:73], v[50:51], v[96:97], v[72:73]
	v_lshl_add_u32 v77, v86, 6, s0
	v_add_f32_e32 v72, v85, v72
	v_add_f32_e32 v76, v72, v73
	s_waitcnt lgkmcnt(0)
	v_mov_b32_e32 v73, v102
	v_mov_b32_e32 v102, v99
	v_mov_b32_e32 v72, v98
	v_pk_mul_f32 v[74:75], v[58:59], v[102:103]
	s_nop 0
	v_pk_fma_f32 v[72:73], v[56:57], v[72:73], v[74:75]
	v_mov_b32_e32 v74, v100
	v_mov_b32_e32 v75, v104
	v_pk_fma_f32 v[72:73], v[64:65], v[74:75], v[72:73]
	v_mov_b32_e32 v104, v101
	v_pk_fma_f32 v[72:73], v[62:63], v[104:105], v[72:73]
	s_nop 0
	v_add_f32_e32 v72, v76, v72
	v_add_f32_e32 v72, v72, v73
	v_max_f32_e32 v72, 0xc2a00000, v72
	v_mul_f32_e32 v72, 0xbfb8aa3b, v72
	v_exp_f32_e32 v72, v72
	v_lshl_add_u32 v73, v70, 10, v68
	ds_write_b32 v73, v69
	v_add_f32_e32 v72, 1.0, v72
	v_log_f32_e32 v76, v72
	ds_read_b128 v[72:75], v77
	ds_read_b128 v[94:97], v77 offset:16
	ds_read_b128 v[98:101], v77 offset:32
	ds_read_b128 v[102:105], v77 offset:48
	v_mul_f32_e32 v87, 0x3f317218, v76
	s_waitcnt lgkmcnt(3)
	v_mov_b32_e32 v76, v72
	s_waitcnt lgkmcnt(2)
	v_mov_b32_e32 v77, v94
	v_mov_b32_e32 v94, v73
	v_pk_mul_f32 v[72:73], v[54:55], v[94:95]
	v_fmac_f32_e32 v69, 0xbd800000, v87
	v_pk_fma_f32 v[72:73], v[52:53], v[76:77], v[72:73]
	v_mov_b32_e32 v76, v74
	v_mov_b32_e32 v77, v96
	v_pk_fma_f32 v[72:73], v[60:61], v[76:77], v[72:73]
	v_mov_b32_e32 v96, v75
	v_pk_fma_f32 v[72:73], v[50:51], v[96:97], v[72:73]
	v_or_b32_e32 v87, 3, v70
	v_add_f32_e32 v72, v85, v72
	v_add_f32_e32 v76, v72, v73
	s_waitcnt lgkmcnt(0)
	v_mov_b32_e32 v73, v102
	v_mov_b32_e32 v102, v99
	v_mov_b32_e32 v72, v98
	v_pk_mul_f32 v[74:75], v[58:59], v[102:103]
	ds_write_b32 v71, v69
	v_pk_fma_f32 v[72:73], v[56:57], v[72:73], v[74:75]
	v_mov_b32_e32 v74, v100
	v_mov_b32_e32 v75, v104
	v_pk_fma_f32 v[72:73], v[64:65], v[74:75], v[72:73]
	v_mov_b32_e32 v104, v101
	v_pk_fma_f32 v[72:73], v[62:63], v[104:105], v[72:73]
	s_nop 0
	v_add_f32_e32 v72, v76, v72
	v_add_f32_e32 v72, v72, v73
	v_max_f32_e32 v72, 0xc2a00000, v72
	v_mul_f32_e32 v72, 0xbfb8aa3b, v72
	v_exp_f32_e32 v72, v72
	v_lshl_add_u32 v76, v87, 6, s0
	v_add_f32_e32 v71, 1.0, v72
	ds_read_b128 v[72:75], v76
	ds_read_b128 v[94:97], v76 offset:16
	ds_read_b128 v[98:101], v76 offset:32
	ds_read_b128 v[102:105], v76 offset:48
	v_log_f32_e32 v71, v71
	s_waitcnt lgkmcnt(3)
	v_mov_b32_e32 v76, v72
	s_waitcnt lgkmcnt(2)
	v_mov_b32_e32 v77, v94
	v_mov_b32_e32 v94, v73
	v_pk_mul_f32 v[72:73], v[54:55], v[94:95]
	v_mul_f32_e32 v71, 0x3f317218, v71
	v_pk_fma_f32 v[72:73], v[52:53], v[76:77], v[72:73]
	v_mov_b32_e32 v76, v74
	v_mov_b32_e32 v77, v96
	v_pk_fma_f32 v[72:73], v[60:61], v[76:77], v[72:73]
	v_mov_b32_e32 v96, v75
	v_pk_fma_f32 v[72:73], v[50:51], v[96:97], v[72:73]
	v_fmac_f32_e32 v69, 0xbd800000, v71
	v_add_f32_e32 v72, v85, v72
	v_add_f32_e32 v76, v72, v73
	s_waitcnt lgkmcnt(0)
	v_mov_b32_e32 v73, v102
	v_mov_b32_e32 v102, v99
	v_mov_b32_e32 v72, v98
	v_pk_mul_f32 v[74:75], v[58:59], v[102:103]
	v_lshl_add_u32 v71, v86, 10, v68
	v_pk_fma_f32 v[72:73], v[56:57], v[72:73], v[74:75]
	v_mov_b32_e32 v74, v100
	v_mov_b32_e32 v75, v104
	v_pk_fma_f32 v[72:73], v[64:65], v[74:75], v[72:73]
	v_mov_b32_e32 v104, v101
	v_pk_fma_f32 v[72:73], v[62:63], v[104:105], v[72:73]
	v_or_b32_e32 v86, 4, v70
	v_add_f32_e32 v72, v76, v72
	v_add_f32_e32 v72, v72, v73
	v_max_f32_e32 v72, 0xc2a00000, v72
	v_mul_f32_e32 v72, 0xbfb8aa3b, v72
	v_exp_f32_e32 v72, v72
	ds_write_b32 v71, v69
	v_lshl_add_u32 v76, v86, 6, s0
	v_add_f32_e32 v71, 1.0, v72
	ds_read_b128 v[72:75], v76
	ds_read_b128 v[94:97], v76 offset:16
	ds_read_b128 v[98:101], v76 offset:32
	ds_read_b128 v[102:105], v76 offset:48
	v_log_f32_e32 v71, v71
	s_waitcnt lgkmcnt(3)
	v_mov_b32_e32 v76, v72
	s_waitcnt lgkmcnt(2)
	v_mov_b32_e32 v77, v94
	v_mov_b32_e32 v94, v73
	v_pk_mul_f32 v[72:73], v[54:55], v[94:95]
	v_mul_f32_e32 v71, 0x3f317218, v71
	v_pk_fma_f32 v[72:73], v[52:53], v[76:77], v[72:73]
	v_mov_b32_e32 v76, v74
	v_mov_b32_e32 v77, v96
	v_pk_fma_f32 v[72:73], v[60:61], v[76:77], v[72:73]
	v_mov_b32_e32 v96, v75
	v_pk_fma_f32 v[72:73], v[50:51], v[96:97], v[72:73]
	v_fmac_f32_e32 v69, 0xbd800000, v71
	v_add_f32_e32 v72, v85, v72
	v_add_f32_e32 v76, v72, v73
	s_waitcnt lgkmcnt(0)
	v_mov_b32_e32 v73, v102
	v_mov_b32_e32 v102, v99
	v_mov_b32_e32 v72, v98
	v_pk_mul_f32 v[74:75], v[58:59], v[102:103]
	v_lshl_add_u32 v71, v87, 10, v68
	v_pk_fma_f32 v[72:73], v[56:57], v[72:73], v[74:75]
	v_mov_b32_e32 v74, v100
	v_mov_b32_e32 v75, v104
	v_pk_fma_f32 v[72:73], v[64:65], v[74:75], v[72:73]
	v_mov_b32_e32 v104, v101
	v_pk_fma_f32 v[72:73], v[62:63], v[104:105], v[72:73]
	v_or_b32_e32 v87, 5, v70
	v_add_f32_e32 v72, v76, v72
	v_add_f32_e32 v72, v72, v73
	v_max_f32_e32 v72, 0xc2a00000, v72
	v_mul_f32_e32 v72, 0xbfb8aa3b, v72
	v_exp_f32_e32 v72, v72
	ds_write_b32 v71, v69
	v_lshl_add_u32 v76, v87, 6, s0
	v_add_f32_e32 v71, 1.0, v72
	ds_read_b128 v[72:75], v76
	ds_read_b128 v[94:97], v76 offset:16
	ds_read_b128 v[98:101], v76 offset:32
	ds_read_b128 v[102:105], v76 offset:48
	v_log_f32_e32 v71, v71
	s_waitcnt lgkmcnt(3)
	v_mov_b32_e32 v76, v72
	s_waitcnt lgkmcnt(2)
	v_mov_b32_e32 v77, v94
	v_mov_b32_e32 v94, v73
	v_pk_mul_f32 v[72:73], v[54:55], v[94:95]
	v_mul_f32_e32 v71, 0x3f317218, v71
	v_pk_fma_f32 v[72:73], v[52:53], v[76:77], v[72:73]
	v_mov_b32_e32 v76, v74
	v_mov_b32_e32 v77, v96
	v_pk_fma_f32 v[72:73], v[60:61], v[76:77], v[72:73]
	v_mov_b32_e32 v96, v75
	v_pk_fma_f32 v[72:73], v[50:51], v[96:97], v[72:73]
	v_fmac_f32_e32 v69, 0xbd800000, v71
	v_add_f32_e32 v72, v85, v72
	v_add_f32_e32 v76, v72, v73
	s_waitcnt lgkmcnt(0)
	v_mov_b32_e32 v73, v102
	v_mov_b32_e32 v102, v99
	v_mov_b32_e32 v72, v98
	v_pk_mul_f32 v[74:75], v[58:59], v[102:103]
	v_lshl_add_u32 v71, v86, 10, v68
	v_pk_fma_f32 v[72:73], v[56:57], v[72:73], v[74:75]
	v_mov_b32_e32 v74, v100
	v_mov_b32_e32 v75, v104
	v_pk_fma_f32 v[72:73], v[64:65], v[74:75], v[72:73]
	v_mov_b32_e32 v104, v101
	v_pk_fma_f32 v[72:73], v[62:63], v[104:105], v[72:73]
	v_or_b32_e32 v86, 6, v70
	v_add_f32_e32 v72, v76, v72
	v_add_f32_e32 v72, v72, v73
	v_max_f32_e32 v72, 0xc2a00000, v72
	v_mul_f32_e32 v72, 0xbfb8aa3b, v72
	v_exp_f32_e32 v72, v72
	ds_write_b32 v71, v69
	v_lshl_add_u32 v76, v86, 6, s0
	v_add_f32_e32 v71, 1.0, v72
	ds_read_b128 v[72:75], v76
	ds_read_b128 v[94:97], v76 offset:16
	ds_read_b128 v[98:101], v76 offset:32
	ds_read_b128 v[102:105], v76 offset:48
	v_log_f32_e32 v71, v71
	s_waitcnt lgkmcnt(3)
	v_mov_b32_e32 v76, v72
	s_waitcnt lgkmcnt(2)
	v_mov_b32_e32 v77, v94
	v_mov_b32_e32 v94, v73
	v_pk_mul_f32 v[72:73], v[54:55], v[94:95]
	v_mul_f32_e32 v71, 0x3f317218, v71
	v_pk_fma_f32 v[72:73], v[52:53], v[76:77], v[72:73]
	v_mov_b32_e32 v76, v74
	v_mov_b32_e32 v77, v96
	v_pk_fma_f32 v[72:73], v[60:61], v[76:77], v[72:73]
	v_mov_b32_e32 v96, v75
	v_pk_fma_f32 v[72:73], v[50:51], v[96:97], v[72:73]
	v_fmac_f32_e32 v69, 0xbd800000, v71
	v_add_f32_e32 v72, v85, v72
	v_add_f32_e32 v76, v72, v73
	s_waitcnt lgkmcnt(0)
	v_mov_b32_e32 v73, v102
	v_mov_b32_e32 v102, v99
	v_mov_b32_e32 v72, v98
	v_pk_mul_f32 v[74:75], v[58:59], v[102:103]
	v_lshl_add_u32 v71, v87, 10, v68
	v_pk_fma_f32 v[72:73], v[56:57], v[72:73], v[74:75]
	v_mov_b32_e32 v74, v100
	v_mov_b32_e32 v75, v104
	v_pk_fma_f32 v[72:73], v[64:65], v[74:75], v[72:73]
	v_mov_b32_e32 v104, v101
	v_pk_fma_f32 v[72:73], v[62:63], v[104:105], v[72:73]
	v_or_b32_e32 v87, 7, v70
	v_add_f32_e32 v72, v76, v72
	v_add_f32_e32 v72, v72, v73
	v_max_f32_e32 v72, 0xc2a00000, v72
	v_mul_f32_e32 v72, 0xbfb8aa3b, v72
	v_exp_f32_e32 v72, v72
	ds_write_b32 v71, v69
	v_lshl_add_u32 v76, v87, 6, s0
	v_add_f32_e32 v71, 1.0, v72
	ds_read_b128 v[72:75], v76
	ds_read_b128 v[94:97], v76 offset:16
	ds_read_b128 v[98:101], v76 offset:32
	ds_read_b128 v[102:105], v76 offset:48
	v_log_f32_e32 v71, v71
	s_waitcnt lgkmcnt(3)
	v_mov_b32_e32 v76, v72
	s_waitcnt lgkmcnt(2)
	v_mov_b32_e32 v77, v94
	v_mov_b32_e32 v94, v73
	v_pk_mul_f32 v[72:73], v[54:55], v[94:95]
	v_mul_f32_e32 v71, 0x3f317218, v71
	v_pk_fma_f32 v[72:73], v[52:53], v[76:77], v[72:73]
	v_mov_b32_e32 v76, v74
	v_mov_b32_e32 v77, v96
	v_pk_fma_f32 v[72:73], v[60:61], v[76:77], v[72:73]
	v_mov_b32_e32 v96, v75
	v_pk_fma_f32 v[72:73], v[50:51], v[96:97], v[72:73]
	v_fmac_f32_e32 v69, 0xbd800000, v71
	v_add_f32_e32 v72, v85, v72
	v_add_f32_e32 v76, v72, v73
	s_waitcnt lgkmcnt(0)
	v_mov_b32_e32 v73, v102
	v_mov_b32_e32 v102, v99
	v_mov_b32_e32 v72, v98
	v_pk_mul_f32 v[74:75], v[58:59], v[102:103]
	v_lshl_add_u32 v71, v86, 10, v68
	v_pk_fma_f32 v[72:73], v[56:57], v[72:73], v[74:75]
	v_mov_b32_e32 v74, v100
	v_mov_b32_e32 v75, v104
	v_pk_fma_f32 v[72:73], v[64:65], v[74:75], v[72:73]
	v_mov_b32_e32 v104, v101
	v_pk_fma_f32 v[72:73], v[62:63], v[104:105], v[72:73]
	v_or_b32_e32 v86, 8, v70
	v_add_f32_e32 v72, v76, v72
	v_add_f32_e32 v72, v72, v73
	v_max_f32_e32 v72, 0xc2a00000, v72
	v_mul_f32_e32 v72, 0xbfb8aa3b, v72
	v_exp_f32_e32 v72, v72
	ds_write_b32 v71, v69
	v_lshl_add_u32 v76, v86, 6, s0
	v_add_f32_e32 v71, 1.0, v72
	ds_read_b128 v[72:75], v76
	ds_read_b128 v[94:97], v76 offset:16
	ds_read_b128 v[98:101], v76 offset:32
	ds_read_b128 v[102:105], v76 offset:48
	v_log_f32_e32 v71, v71
	s_waitcnt lgkmcnt(3)
	v_mov_b32_e32 v76, v72
	s_waitcnt lgkmcnt(2)
	v_mov_b32_e32 v77, v94
	v_mov_b32_e32 v94, v73
	v_pk_mul_f32 v[72:73], v[54:55], v[94:95]
	v_mul_f32_e32 v71, 0x3f317218, v71
	v_pk_fma_f32 v[72:73], v[52:53], v[76:77], v[72:73]
	v_mov_b32_e32 v76, v74
	v_mov_b32_e32 v77, v96
	v_pk_fma_f32 v[72:73], v[60:61], v[76:77], v[72:73]
	v_mov_b32_e32 v96, v75
	v_pk_fma_f32 v[72:73], v[50:51], v[96:97], v[72:73]
	v_fmac_f32_e32 v69, 0xbd800000, v71
	v_add_f32_e32 v72, v85, v72
	v_add_f32_e32 v76, v72, v73
	s_waitcnt lgkmcnt(0)
	v_mov_b32_e32 v73, v102
	v_mov_b32_e32 v102, v99
	v_mov_b32_e32 v72, v98
	v_pk_mul_f32 v[74:75], v[58:59], v[102:103]
	v_lshl_add_u32 v71, v87, 10, v68
	v_pk_fma_f32 v[72:73], v[56:57], v[72:73], v[74:75]
	v_mov_b32_e32 v74, v100
	v_mov_b32_e32 v75, v104
	v_pk_fma_f32 v[72:73], v[64:65], v[74:75], v[72:73]
	v_mov_b32_e32 v104, v101
	v_pk_fma_f32 v[72:73], v[62:63], v[104:105], v[72:73]
	v_or_b32_e32 v87, 9, v70
	v_add_f32_e32 v72, v76, v72
	v_add_f32_e32 v72, v72, v73
	v_max_f32_e32 v72, 0xc2a00000, v72
	v_mul_f32_e32 v72, 0xbfb8aa3b, v72
	v_exp_f32_e32 v72, v72
	ds_write_b32 v71, v69
	v_lshl_add_u32 v76, v87, 6, s0
	v_add_f32_e32 v71, 1.0, v72
	ds_read_b128 v[72:75], v76
	ds_read_b128 v[94:97], v76 offset:16
	ds_read_b128 v[98:101], v76 offset:32
	ds_read_b128 v[102:105], v76 offset:48
	v_log_f32_e32 v71, v71
	s_waitcnt lgkmcnt(3)
	v_mov_b32_e32 v76, v72
	s_waitcnt lgkmcnt(2)
	v_mov_b32_e32 v77, v94
	v_mov_b32_e32 v94, v73
	v_pk_mul_f32 v[72:73], v[54:55], v[94:95]
	v_mul_f32_e32 v71, 0x3f317218, v71
	v_pk_fma_f32 v[72:73], v[52:53], v[76:77], v[72:73]
	v_mov_b32_e32 v76, v74
	v_mov_b32_e32 v77, v96
	v_pk_fma_f32 v[72:73], v[60:61], v[76:77], v[72:73]
	v_mov_b32_e32 v96, v75
	v_pk_fma_f32 v[72:73], v[50:51], v[96:97], v[72:73]
	v_fmac_f32_e32 v69, 0xbd800000, v71
	v_add_f32_e32 v72, v85, v72
	v_add_f32_e32 v76, v72, v73
	s_waitcnt lgkmcnt(0)
	v_mov_b32_e32 v73, v102
	v_mov_b32_e32 v102, v99
	v_mov_b32_e32 v72, v98
	v_pk_mul_f32 v[74:75], v[58:59], v[102:103]
	v_lshl_add_u32 v71, v86, 10, v68
	v_pk_fma_f32 v[72:73], v[56:57], v[72:73], v[74:75]
	v_mov_b32_e32 v74, v100
	v_mov_b32_e32 v75, v104
	v_pk_fma_f32 v[72:73], v[64:65], v[74:75], v[72:73]
	v_mov_b32_e32 v104, v101
	v_pk_fma_f32 v[72:73], v[62:63], v[104:105], v[72:73]
	v_or_b32_e32 v86, 10, v70
	v_add_f32_e32 v72, v76, v72
	v_add_f32_e32 v72, v72, v73
	v_max_f32_e32 v72, 0xc2a00000, v72
	v_mul_f32_e32 v72, 0xbfb8aa3b, v72
	v_exp_f32_e32 v72, v72
	ds_write_b32 v71, v69
	v_lshl_add_u32 v76, v86, 6, s0
	v_add_f32_e32 v71, 1.0, v72
	ds_read_b128 v[72:75], v76
	ds_read_b128 v[94:97], v76 offset:16
	ds_read_b128 v[98:101], v76 offset:32
	ds_read_b128 v[102:105], v76 offset:48
	v_log_f32_e32 v71, v71
	s_waitcnt lgkmcnt(3)
	v_mov_b32_e32 v76, v72
	s_waitcnt lgkmcnt(2)
	v_mov_b32_e32 v77, v94
	v_mov_b32_e32 v94, v73
	v_pk_mul_f32 v[72:73], v[54:55], v[94:95]
	v_mul_f32_e32 v71, 0x3f317218, v71
	v_pk_fma_f32 v[72:73], v[52:53], v[76:77], v[72:73]
	v_mov_b32_e32 v76, v74
	v_mov_b32_e32 v77, v96
	v_pk_fma_f32 v[72:73], v[60:61], v[76:77], v[72:73]
	v_mov_b32_e32 v96, v75
	v_pk_fma_f32 v[72:73], v[50:51], v[96:97], v[72:73]
	v_fmac_f32_e32 v69, 0xbd800000, v71
	v_add_f32_e32 v72, v85, v72
	v_add_f32_e32 v76, v72, v73
	s_waitcnt lgkmcnt(0)
	v_mov_b32_e32 v73, v102
	v_mov_b32_e32 v102, v99
	v_mov_b32_e32 v72, v98
	v_pk_mul_f32 v[74:75], v[58:59], v[102:103]
	v_lshl_add_u32 v71, v87, 10, v68
	v_pk_fma_f32 v[72:73], v[56:57], v[72:73], v[74:75]
	v_mov_b32_e32 v74, v100
	v_mov_b32_e32 v75, v104
	v_pk_fma_f32 v[72:73], v[64:65], v[74:75], v[72:73]
	v_mov_b32_e32 v104, v101
	v_pk_fma_f32 v[72:73], v[62:63], v[104:105], v[72:73]
	v_or_b32_e32 v87, 11, v70
	v_add_f32_e32 v72, v76, v72
	v_add_f32_e32 v72, v72, v73
	v_max_f32_e32 v72, 0xc2a00000, v72
	v_mul_f32_e32 v72, 0xbfb8aa3b, v72
	v_exp_f32_e32 v72, v72
	ds_write_b32 v71, v69
	v_lshl_add_u32 v76, v87, 6, s0
	v_add_f32_e32 v71, 1.0, v72
	ds_read_b128 v[72:75], v76
	ds_read_b128 v[94:97], v76 offset:16
	ds_read_b128 v[98:101], v76 offset:32
	ds_read_b128 v[102:105], v76 offset:48
	v_log_f32_e32 v71, v71
	s_waitcnt lgkmcnt(3)
	v_mov_b32_e32 v76, v72
	s_waitcnt lgkmcnt(2)
	v_mov_b32_e32 v77, v94
	v_mov_b32_e32 v94, v73
	v_pk_mul_f32 v[72:73], v[54:55], v[94:95]
	v_mul_f32_e32 v71, 0x3f317218, v71
	v_pk_fma_f32 v[72:73], v[52:53], v[76:77], v[72:73]
	v_mov_b32_e32 v76, v74
	v_mov_b32_e32 v77, v96
	v_pk_fma_f32 v[72:73], v[60:61], v[76:77], v[72:73]
	v_mov_b32_e32 v96, v75
	v_pk_fma_f32 v[72:73], v[50:51], v[96:97], v[72:73]
	v_fmac_f32_e32 v69, 0xbd800000, v71
	v_add_f32_e32 v72, v85, v72
	v_add_f32_e32 v76, v72, v73
	s_waitcnt lgkmcnt(0)
	v_mov_b32_e32 v73, v102
	v_mov_b32_e32 v102, v99
	v_mov_b32_e32 v72, v98
	v_pk_mul_f32 v[74:75], v[58:59], v[102:103]
	v_lshl_add_u32 v71, v86, 10, v68
	v_pk_fma_f32 v[72:73], v[56:57], v[72:73], v[74:75]
	v_mov_b32_e32 v74, v100
	v_mov_b32_e32 v75, v104
	v_pk_fma_f32 v[72:73], v[64:65], v[74:75], v[72:73]
	v_mov_b32_e32 v104, v101
	v_pk_fma_f32 v[72:73], v[62:63], v[104:105], v[72:73]
	v_or_b32_e32 v86, 12, v70
	v_add_f32_e32 v72, v76, v72
	v_add_f32_e32 v72, v72, v73
	v_max_f32_e32 v72, 0xc2a00000, v72
	v_mul_f32_e32 v72, 0xbfb8aa3b, v72
	v_exp_f32_e32 v72, v72
	ds_write_b32 v71, v69
	v_lshl_add_u32 v76, v86, 6, s0
	v_add_f32_e32 v71, 1.0, v72
	ds_read_b128 v[72:75], v76
	ds_read_b128 v[94:97], v76 offset:16
	ds_read_b128 v[98:101], v76 offset:32
	ds_read_b128 v[102:105], v76 offset:48
	v_log_f32_e32 v71, v71
	s_waitcnt lgkmcnt(3)
	v_mov_b32_e32 v76, v72
	s_waitcnt lgkmcnt(2)
	v_mov_b32_e32 v77, v94
	v_mov_b32_e32 v94, v73
	v_pk_mul_f32 v[72:73], v[54:55], v[94:95]
	v_mul_f32_e32 v71, 0x3f317218, v71
	v_pk_fma_f32 v[72:73], v[52:53], v[76:77], v[72:73]
	v_mov_b32_e32 v76, v74
	v_mov_b32_e32 v77, v96
	v_pk_fma_f32 v[72:73], v[60:61], v[76:77], v[72:73]
	v_mov_b32_e32 v96, v75
	v_pk_fma_f32 v[72:73], v[50:51], v[96:97], v[72:73]
	v_fmac_f32_e32 v69, 0xbd800000, v71
	v_add_f32_e32 v72, v85, v72
	v_add_f32_e32 v76, v72, v73
	s_waitcnt lgkmcnt(0)
	v_mov_b32_e32 v73, v102
	v_mov_b32_e32 v102, v99
	v_mov_b32_e32 v72, v98
	v_pk_mul_f32 v[74:75], v[58:59], v[102:103]
	v_lshl_add_u32 v71, v87, 10, v68
	v_pk_fma_f32 v[72:73], v[56:57], v[72:73], v[74:75]
	v_mov_b32_e32 v74, v100
	v_mov_b32_e32 v75, v104
	v_pk_fma_f32 v[72:73], v[64:65], v[74:75], v[72:73]
	v_mov_b32_e32 v104, v101
	v_pk_fma_f32 v[72:73], v[62:63], v[104:105], v[72:73]
	v_or_b32_e32 v87, 13, v70
	v_add_f32_e32 v72, v76, v72
	v_add_f32_e32 v72, v72, v73
	v_max_f32_e32 v72, 0xc2a00000, v72
	v_mul_f32_e32 v72, 0xbfb8aa3b, v72
	v_exp_f32_e32 v72, v72
	ds_write_b32 v71, v69
	v_lshl_add_u32 v76, v87, 6, s0
	v_add_f32_e32 v71, 1.0, v72
	ds_read_b128 v[72:75], v76
	ds_read_b128 v[94:97], v76 offset:16
	ds_read_b128 v[98:101], v76 offset:32
	ds_read_b128 v[102:105], v76 offset:48
	v_log_f32_e32 v71, v71
	s_waitcnt lgkmcnt(3)
	v_mov_b32_e32 v76, v72
	s_waitcnt lgkmcnt(2)
	v_mov_b32_e32 v77, v94
	v_mov_b32_e32 v94, v73
	v_pk_mul_f32 v[72:73], v[54:55], v[94:95]
	v_mul_f32_e32 v71, 0x3f317218, v71
	v_pk_fma_f32 v[72:73], v[52:53], v[76:77], v[72:73]
	v_mov_b32_e32 v76, v74
	v_mov_b32_e32 v77, v96
	v_pk_fma_f32 v[72:73], v[60:61], v[76:77], v[72:73]
	v_mov_b32_e32 v96, v75
	v_pk_fma_f32 v[72:73], v[50:51], v[96:97], v[72:73]
	v_fmac_f32_e32 v69, 0xbd800000, v71
	v_add_f32_e32 v72, v85, v72
	v_add_f32_e32 v76, v72, v73
	s_waitcnt lgkmcnt(0)
	v_mov_b32_e32 v73, v102
	v_mov_b32_e32 v102, v99
	v_mov_b32_e32 v72, v98
	v_pk_mul_f32 v[74:75], v[58:59], v[102:103]
	v_lshl_add_u32 v71, v86, 10, v68
	v_pk_fma_f32 v[72:73], v[56:57], v[72:73], v[74:75]
	v_mov_b32_e32 v74, v100
	v_mov_b32_e32 v75, v104
	v_pk_fma_f32 v[72:73], v[64:65], v[74:75], v[72:73]
	v_mov_b32_e32 v104, v101
	v_pk_fma_f32 v[72:73], v[62:63], v[104:105], v[72:73]
	v_or_b32_e32 v86, 14, v70
	v_add_f32_e32 v72, v76, v72
	v_add_f32_e32 v72, v72, v73
	v_max_f32_e32 v72, 0xc2a00000, v72
	v_mul_f32_e32 v72, 0xbfb8aa3b, v72
	v_exp_f32_e32 v72, v72
	ds_write_b32 v71, v69
	v_lshl_add_u32 v76, v86, 6, s0
	v_add_f32_e32 v71, 1.0, v72
	ds_read_b128 v[72:75], v76
	ds_read_b128 v[94:97], v76 offset:16
	ds_read_b128 v[98:101], v76 offset:32
	ds_read_b128 v[102:105], v76 offset:48
	v_log_f32_e32 v71, v71
	s_waitcnt lgkmcnt(3)
	v_mov_b32_e32 v76, v72
	s_waitcnt lgkmcnt(2)
	v_mov_b32_e32 v77, v94
	v_mov_b32_e32 v94, v73
	v_pk_mul_f32 v[72:73], v[54:55], v[94:95]
	v_mul_f32_e32 v71, 0x3f317218, v71
	v_pk_fma_f32 v[72:73], v[52:53], v[76:77], v[72:73]
	v_mov_b32_e32 v76, v74
	v_mov_b32_e32 v77, v96
	v_pk_fma_f32 v[72:73], v[60:61], v[76:77], v[72:73]
	v_mov_b32_e32 v96, v75
	v_pk_fma_f32 v[72:73], v[50:51], v[96:97], v[72:73]
	v_fmac_f32_e32 v69, 0xbd800000, v71
	v_add_f32_e32 v72, v85, v72
	v_add_f32_e32 v76, v72, v73
	s_waitcnt lgkmcnt(0)
	v_mov_b32_e32 v73, v102
	v_mov_b32_e32 v102, v99
	v_mov_b32_e32 v72, v98
	v_pk_mul_f32 v[74:75], v[58:59], v[102:103]
	v_lshl_add_u32 v71, v87, 10, v68
	v_pk_fma_f32 v[72:73], v[56:57], v[72:73], v[74:75]
	v_mov_b32_e32 v74, v100
	v_mov_b32_e32 v75, v104
	v_pk_fma_f32 v[72:73], v[64:65], v[74:75], v[72:73]
	v_mov_b32_e32 v104, v101
	v_pk_fma_f32 v[72:73], v[62:63], v[104:105], v[72:73]
	v_or_b32_e32 v87, 15, v70
	v_add_f32_e32 v72, v76, v72
	v_add_f32_e32 v72, v72, v73
	v_max_f32_e32 v72, 0xc2a00000, v72
	v_mul_f32_e32 v72, 0xbfb8aa3b, v72
	v_exp_f32_e32 v72, v72
	ds_write_b32 v71, v69
	v_lshl_add_u32 v76, v87, 6, s0
	v_add_f32_e32 v71, 1.0, v72
	ds_read_b128 v[72:75], v76
	ds_read_b128 v[94:97], v76 offset:16
	ds_read_b128 v[98:101], v76 offset:32
	ds_read_b128 v[102:105], v76 offset:48
	v_log_f32_e32 v71, v71
	s_waitcnt lgkmcnt(3)
	v_mov_b32_e32 v76, v72
	s_waitcnt lgkmcnt(2)
	v_mov_b32_e32 v77, v94
	v_mov_b32_e32 v94, v73
	v_pk_mul_f32 v[72:73], v[54:55], v[94:95]
	v_mul_f32_e32 v71, 0x3f317218, v71
	v_pk_fma_f32 v[72:73], v[52:53], v[76:77], v[72:73]
	v_mov_b32_e32 v76, v74
	v_mov_b32_e32 v77, v96
	v_pk_fma_f32 v[72:73], v[60:61], v[76:77], v[72:73]
	v_mov_b32_e32 v96, v75
	v_pk_fma_f32 v[72:73], v[50:51], v[96:97], v[72:73]
	v_fmac_f32_e32 v69, 0xbd800000, v71
	v_add_f32_e32 v72, v85, v72
	v_add_f32_e32 v76, v72, v73
	s_waitcnt lgkmcnt(0)
	v_mov_b32_e32 v73, v102
	v_mov_b32_e32 v102, v99
	v_mov_b32_e32 v72, v98
	v_pk_mul_f32 v[74:75], v[58:59], v[102:103]
	v_lshl_add_u32 v71, v86, 10, v68
	v_pk_fma_f32 v[72:73], v[56:57], v[72:73], v[74:75]
	v_mov_b32_e32 v74, v100
	v_mov_b32_e32 v75, v104
	v_pk_fma_f32 v[72:73], v[64:65], v[74:75], v[72:73]
	v_mov_b32_e32 v104, v101
	v_pk_fma_f32 v[72:73], v[62:63], v[104:105], v[72:73]
	v_or_b32_e32 v86, 16, v70
	v_add_f32_e32 v72, v76, v72
	v_add_f32_e32 v72, v72, v73
	v_max_f32_e32 v72, 0xc2a00000, v72
	v_mul_f32_e32 v72, 0xbfb8aa3b, v72
	v_exp_f32_e32 v72, v72
	ds_write_b32 v71, v69
	v_lshl_add_u32 v76, v86, 6, s0
	v_add_f32_e32 v71, 1.0, v72
	ds_read_b128 v[72:75], v76
	ds_read_b128 v[94:97], v76 offset:16
	ds_read_b128 v[98:101], v76 offset:32
	ds_read_b128 v[102:105], v76 offset:48
	v_log_f32_e32 v71, v71
	s_waitcnt lgkmcnt(3)
	v_mov_b32_e32 v76, v72
	s_waitcnt lgkmcnt(2)
	v_mov_b32_e32 v77, v94
	v_mov_b32_e32 v94, v73
	v_pk_mul_f32 v[72:73], v[54:55], v[94:95]
	v_mul_f32_e32 v71, 0x3f317218, v71
	v_pk_fma_f32 v[72:73], v[52:53], v[76:77], v[72:73]
	v_mov_b32_e32 v76, v74
	v_mov_b32_e32 v77, v96
	v_pk_fma_f32 v[72:73], v[60:61], v[76:77], v[72:73]
	v_mov_b32_e32 v96, v75
	v_pk_fma_f32 v[72:73], v[50:51], v[96:97], v[72:73]
	v_fmac_f32_e32 v69, 0xbd800000, v71
	v_add_f32_e32 v72, v85, v72
	v_add_f32_e32 v76, v72, v73
	s_waitcnt lgkmcnt(0)
	v_mov_b32_e32 v73, v102
	v_mov_b32_e32 v102, v99
	v_mov_b32_e32 v72, v98
	v_pk_mul_f32 v[74:75], v[58:59], v[102:103]
	v_lshl_add_u32 v71, v87, 10, v68
	v_pk_fma_f32 v[72:73], v[56:57], v[72:73], v[74:75]
	v_mov_b32_e32 v74, v100
	v_mov_b32_e32 v75, v104
	v_pk_fma_f32 v[72:73], v[64:65], v[74:75], v[72:73]
	v_mov_b32_e32 v104, v101
	v_pk_fma_f32 v[72:73], v[62:63], v[104:105], v[72:73]
	v_or_b32_e32 v87, 17, v70
	v_add_f32_e32 v72, v76, v72
	v_add_f32_e32 v72, v72, v73
	v_max_f32_e32 v72, 0xc2a00000, v72
	v_mul_f32_e32 v72, 0xbfb8aa3b, v72
	v_exp_f32_e32 v72, v72
	ds_write_b32 v71, v69
	v_lshl_add_u32 v76, v87, 6, s0
	v_add_f32_e32 v71, 1.0, v72
	ds_read_b128 v[72:75], v76
	ds_read_b128 v[94:97], v76 offset:16
	ds_read_b128 v[98:101], v76 offset:32
	ds_read_b128 v[102:105], v76 offset:48
	v_log_f32_e32 v71, v71
	s_waitcnt lgkmcnt(3)
	v_mov_b32_e32 v76, v72
	s_waitcnt lgkmcnt(2)
	v_mov_b32_e32 v77, v94
	v_mov_b32_e32 v94, v73
	v_pk_mul_f32 v[72:73], v[54:55], v[94:95]
	v_mul_f32_e32 v71, 0x3f317218, v71
	v_pk_fma_f32 v[72:73], v[52:53], v[76:77], v[72:73]
	v_mov_b32_e32 v76, v74
	v_mov_b32_e32 v77, v96
	v_pk_fma_f32 v[72:73], v[60:61], v[76:77], v[72:73]
	v_mov_b32_e32 v96, v75
	v_pk_fma_f32 v[72:73], v[50:51], v[96:97], v[72:73]
	v_fmac_f32_e32 v69, 0xbd800000, v71
	v_add_f32_e32 v72, v85, v72
	v_add_f32_e32 v76, v72, v73
	s_waitcnt lgkmcnt(0)
	v_mov_b32_e32 v73, v102
	v_mov_b32_e32 v102, v99
	v_mov_b32_e32 v72, v98
	v_pk_mul_f32 v[74:75], v[58:59], v[102:103]
	v_lshl_add_u32 v71, v86, 10, v68
	v_pk_fma_f32 v[72:73], v[56:57], v[72:73], v[74:75]
	v_mov_b32_e32 v74, v100
	v_mov_b32_e32 v75, v104
	v_pk_fma_f32 v[72:73], v[64:65], v[74:75], v[72:73]
	v_mov_b32_e32 v104, v101
	v_pk_fma_f32 v[72:73], v[62:63], v[104:105], v[72:73]
	v_or_b32_e32 v86, 18, v70
	v_add_f32_e32 v72, v76, v72
	v_add_f32_e32 v72, v72, v73
	v_max_f32_e32 v72, 0xc2a00000, v72
	v_mul_f32_e32 v72, 0xbfb8aa3b, v72
	v_exp_f32_e32 v72, v72
	ds_write_b32 v71, v69
	v_lshl_add_u32 v76, v86, 6, s0
	v_add_f32_e32 v71, 1.0, v72
	ds_read_b128 v[72:75], v76
	ds_read_b128 v[94:97], v76 offset:16
	ds_read_b128 v[98:101], v76 offset:32
	ds_read_b128 v[102:105], v76 offset:48
	v_log_f32_e32 v71, v71
	s_waitcnt lgkmcnt(3)
	v_mov_b32_e32 v76, v72
	s_waitcnt lgkmcnt(2)
	v_mov_b32_e32 v77, v94
	v_mov_b32_e32 v94, v73
	v_pk_mul_f32 v[72:73], v[54:55], v[94:95]
	v_mul_f32_e32 v71, 0x3f317218, v71
	v_pk_fma_f32 v[72:73], v[52:53], v[76:77], v[72:73]
	v_mov_b32_e32 v76, v74
	v_mov_b32_e32 v77, v96
	v_pk_fma_f32 v[72:73], v[60:61], v[76:77], v[72:73]
	v_mov_b32_e32 v96, v75
	v_pk_fma_f32 v[72:73], v[50:51], v[96:97], v[72:73]
	v_fmac_f32_e32 v69, 0xbd800000, v71
	v_add_f32_e32 v72, v85, v72
	v_add_f32_e32 v76, v72, v73
	s_waitcnt lgkmcnt(0)
	v_mov_b32_e32 v73, v102
	v_mov_b32_e32 v102, v99
	v_mov_b32_e32 v72, v98
	v_pk_mul_f32 v[74:75], v[58:59], v[102:103]
	v_lshl_add_u32 v71, v87, 10, v68
	v_pk_fma_f32 v[72:73], v[56:57], v[72:73], v[74:75]
	v_mov_b32_e32 v74, v100
	v_mov_b32_e32 v75, v104
	v_pk_fma_f32 v[72:73], v[64:65], v[74:75], v[72:73]
	v_mov_b32_e32 v104, v101
	v_pk_fma_f32 v[72:73], v[62:63], v[104:105], v[72:73]
	v_or_b32_e32 v87, 19, v70
	v_add_f32_e32 v72, v76, v72
	v_add_f32_e32 v72, v72, v73
	v_max_f32_e32 v72, 0xc2a00000, v72
	v_mul_f32_e32 v72, 0xbfb8aa3b, v72
	v_exp_f32_e32 v72, v72
	ds_write_b32 v71, v69
	v_lshl_add_u32 v76, v87, 6, s0
	v_add_f32_e32 v71, 1.0, v72
	ds_read_b128 v[72:75], v76
	ds_read_b128 v[94:97], v76 offset:16
	ds_read_b128 v[98:101], v76 offset:32
	ds_read_b128 v[102:105], v76 offset:48
	v_log_f32_e32 v71, v71
	s_waitcnt lgkmcnt(3)
	v_mov_b32_e32 v76, v72
	s_waitcnt lgkmcnt(2)
	v_mov_b32_e32 v77, v94
	v_mov_b32_e32 v94, v73
	v_pk_mul_f32 v[72:73], v[54:55], v[94:95]
	v_mul_f32_e32 v71, 0x3f317218, v71
	v_pk_fma_f32 v[72:73], v[52:53], v[76:77], v[72:73]
	v_mov_b32_e32 v76, v74
	v_mov_b32_e32 v77, v96
	v_pk_fma_f32 v[72:73], v[60:61], v[76:77], v[72:73]
	v_mov_b32_e32 v96, v75
	v_pk_fma_f32 v[72:73], v[50:51], v[96:97], v[72:73]
	v_fmac_f32_e32 v69, 0xbd800000, v71
	v_add_f32_e32 v72, v85, v72
	v_add_f32_e32 v76, v72, v73
	s_waitcnt lgkmcnt(0)
	v_mov_b32_e32 v73, v102
	v_mov_b32_e32 v102, v99
	v_mov_b32_e32 v72, v98
	v_pk_mul_f32 v[74:75], v[58:59], v[102:103]
	v_lshl_add_u32 v71, v86, 10, v68
	v_pk_fma_f32 v[72:73], v[56:57], v[72:73], v[74:75]
	v_mov_b32_e32 v74, v100
	v_mov_b32_e32 v75, v104
	v_pk_fma_f32 v[72:73], v[64:65], v[74:75], v[72:73]
	v_mov_b32_e32 v104, v101
	v_pk_fma_f32 v[72:73], v[62:63], v[104:105], v[72:73]
	v_or_b32_e32 v86, 20, v70
	v_add_f32_e32 v72, v76, v72
	v_add_f32_e32 v72, v72, v73
	v_max_f32_e32 v72, 0xc2a00000, v72
	v_mul_f32_e32 v72, 0xbfb8aa3b, v72
	v_exp_f32_e32 v72, v72
	ds_write_b32 v71, v69
	v_lshl_add_u32 v76, v86, 6, s0
	v_add_f32_e32 v71, 1.0, v72
	ds_read_b128 v[72:75], v76
	ds_read_b128 v[94:97], v76 offset:16
	ds_read_b128 v[98:101], v76 offset:32
	ds_read_b128 v[102:105], v76 offset:48
	v_log_f32_e32 v71, v71
	s_waitcnt lgkmcnt(3)
	v_mov_b32_e32 v76, v72
	s_waitcnt lgkmcnt(2)
	v_mov_b32_e32 v77, v94
	v_mov_b32_e32 v94, v73
	v_pk_mul_f32 v[72:73], v[54:55], v[94:95]
	v_mul_f32_e32 v71, 0x3f317218, v71
	v_pk_fma_f32 v[72:73], v[52:53], v[76:77], v[72:73]
	v_mov_b32_e32 v76, v74
	v_mov_b32_e32 v77, v96
	v_pk_fma_f32 v[72:73], v[60:61], v[76:77], v[72:73]
	v_mov_b32_e32 v96, v75
	v_pk_fma_f32 v[72:73], v[50:51], v[96:97], v[72:73]
	v_fmac_f32_e32 v69, 0xbd800000, v71
	v_add_f32_e32 v72, v85, v72
	v_add_f32_e32 v76, v72, v73
	s_waitcnt lgkmcnt(0)
	v_mov_b32_e32 v73, v102
	v_mov_b32_e32 v102, v99
	v_mov_b32_e32 v72, v98
	v_pk_mul_f32 v[74:75], v[58:59], v[102:103]
	v_lshl_add_u32 v71, v87, 10, v68
	v_pk_fma_f32 v[72:73], v[56:57], v[72:73], v[74:75]
	v_mov_b32_e32 v74, v100
	v_mov_b32_e32 v75, v104
	v_pk_fma_f32 v[72:73], v[64:65], v[74:75], v[72:73]
	v_mov_b32_e32 v104, v101
	v_pk_fma_f32 v[72:73], v[62:63], v[104:105], v[72:73]
	v_or_b32_e32 v87, 21, v70
	v_add_f32_e32 v72, v76, v72
	v_add_f32_e32 v72, v72, v73
	v_max_f32_e32 v72, 0xc2a00000, v72
	v_mul_f32_e32 v72, 0xbfb8aa3b, v72
	v_exp_f32_e32 v72, v72
	ds_write_b32 v71, v69
	v_lshl_add_u32 v76, v87, 6, s0
	v_add_f32_e32 v71, 1.0, v72
	ds_read_b128 v[72:75], v76
	ds_read_b128 v[94:97], v76 offset:16
	ds_read_b128 v[98:101], v76 offset:32
	ds_read_b128 v[102:105], v76 offset:48
	v_log_f32_e32 v71, v71
	s_waitcnt lgkmcnt(3)
	v_mov_b32_e32 v76, v72
	s_waitcnt lgkmcnt(2)
	v_mov_b32_e32 v77, v94
	v_mov_b32_e32 v94, v73
	v_pk_mul_f32 v[72:73], v[54:55], v[94:95]
	v_mul_f32_e32 v71, 0x3f317218, v71
	v_pk_fma_f32 v[72:73], v[52:53], v[76:77], v[72:73]
	v_mov_b32_e32 v76, v74
	v_mov_b32_e32 v77, v96
	v_pk_fma_f32 v[72:73], v[60:61], v[76:77], v[72:73]
	v_mov_b32_e32 v96, v75
	v_pk_fma_f32 v[72:73], v[50:51], v[96:97], v[72:73]
	v_fmac_f32_e32 v69, 0xbd800000, v71
	v_add_f32_e32 v72, v85, v72
	v_add_f32_e32 v76, v72, v73
	s_waitcnt lgkmcnt(0)
	v_mov_b32_e32 v73, v102
	v_mov_b32_e32 v102, v99
	v_mov_b32_e32 v72, v98
	v_pk_mul_f32 v[74:75], v[58:59], v[102:103]
	v_lshl_add_u32 v71, v86, 10, v68
	v_pk_fma_f32 v[72:73], v[56:57], v[72:73], v[74:75]
	v_mov_b32_e32 v74, v100
	v_mov_b32_e32 v75, v104
	v_pk_fma_f32 v[72:73], v[64:65], v[74:75], v[72:73]
	v_mov_b32_e32 v104, v101
	v_pk_fma_f32 v[72:73], v[62:63], v[104:105], v[72:73]
	v_or_b32_e32 v86, 22, v70
	v_add_f32_e32 v72, v76, v72
	v_add_f32_e32 v72, v72, v73
	v_max_f32_e32 v72, 0xc2a00000, v72
	v_mul_f32_e32 v72, 0xbfb8aa3b, v72
	v_exp_f32_e32 v72, v72
	ds_write_b32 v71, v69
	v_lshl_add_u32 v76, v86, 6, s0
	v_add_f32_e32 v71, 1.0, v72
	ds_read_b128 v[72:75], v76
	ds_read_b128 v[94:97], v76 offset:16
	ds_read_b128 v[98:101], v76 offset:32
	ds_read_b128 v[102:105], v76 offset:48
	v_log_f32_e32 v71, v71
	s_waitcnt lgkmcnt(3)
	v_mov_b32_e32 v76, v72
	s_waitcnt lgkmcnt(2)
	v_mov_b32_e32 v77, v94
	v_mov_b32_e32 v94, v73
	v_pk_mul_f32 v[72:73], v[54:55], v[94:95]
	v_mul_f32_e32 v71, 0x3f317218, v71
	v_pk_fma_f32 v[72:73], v[52:53], v[76:77], v[72:73]
	v_mov_b32_e32 v76, v74
	v_mov_b32_e32 v77, v96
	v_pk_fma_f32 v[72:73], v[60:61], v[76:77], v[72:73]
	v_mov_b32_e32 v96, v75
	v_pk_fma_f32 v[72:73], v[50:51], v[96:97], v[72:73]
	v_fmac_f32_e32 v69, 0xbd800000, v71
	v_add_f32_e32 v72, v85, v72
	v_add_f32_e32 v76, v72, v73
	s_waitcnt lgkmcnt(0)
	v_mov_b32_e32 v73, v102
	v_mov_b32_e32 v102, v99
	v_mov_b32_e32 v72, v98
	v_pk_mul_f32 v[74:75], v[58:59], v[102:103]
	v_lshl_add_u32 v71, v87, 10, v68
	v_pk_fma_f32 v[72:73], v[56:57], v[72:73], v[74:75]
	v_mov_b32_e32 v74, v100
	v_mov_b32_e32 v75, v104
	v_pk_fma_f32 v[72:73], v[64:65], v[74:75], v[72:73]
	v_mov_b32_e32 v104, v101
	v_pk_fma_f32 v[72:73], v[62:63], v[104:105], v[72:73]
	v_or_b32_e32 v87, 23, v70
	v_add_f32_e32 v72, v76, v72
	v_add_f32_e32 v72, v72, v73
	v_max_f32_e32 v72, 0xc2a00000, v72
	v_mul_f32_e32 v72, 0xbfb8aa3b, v72
	v_exp_f32_e32 v72, v72
	ds_write_b32 v71, v69
	v_lshl_add_u32 v76, v87, 6, s0
	v_add_f32_e32 v71, 1.0, v72
	ds_read_b128 v[72:75], v76
	ds_read_b128 v[94:97], v76 offset:16
	ds_read_b128 v[98:101], v76 offset:32
	ds_read_b128 v[102:105], v76 offset:48
	v_log_f32_e32 v71, v71
	s_waitcnt lgkmcnt(3)
	v_mov_b32_e32 v76, v72
	s_waitcnt lgkmcnt(2)
	v_mov_b32_e32 v77, v94
	v_mov_b32_e32 v94, v73
	v_pk_mul_f32 v[72:73], v[54:55], v[94:95]
	v_mul_f32_e32 v71, 0x3f317218, v71
	v_pk_fma_f32 v[72:73], v[52:53], v[76:77], v[72:73]
	v_mov_b32_e32 v76, v74
	v_mov_b32_e32 v77, v96
	v_pk_fma_f32 v[72:73], v[60:61], v[76:77], v[72:73]
	v_mov_b32_e32 v96, v75
	v_pk_fma_f32 v[72:73], v[50:51], v[96:97], v[72:73]
	v_fmac_f32_e32 v69, 0xbd800000, v71
	v_add_f32_e32 v72, v85, v72
	v_add_f32_e32 v76, v72, v73
	s_waitcnt lgkmcnt(0)
	v_mov_b32_e32 v73, v102
	v_mov_b32_e32 v102, v99
	v_mov_b32_e32 v72, v98
	v_pk_mul_f32 v[74:75], v[58:59], v[102:103]
	v_lshl_add_u32 v71, v86, 10, v68
	v_pk_fma_f32 v[72:73], v[56:57], v[72:73], v[74:75]
	v_mov_b32_e32 v74, v100
	v_mov_b32_e32 v75, v104
	v_pk_fma_f32 v[72:73], v[64:65], v[74:75], v[72:73]
	v_mov_b32_e32 v104, v101
	v_pk_fma_f32 v[72:73], v[62:63], v[104:105], v[72:73]
	v_or_b32_e32 v86, 24, v70
	v_add_f32_e32 v72, v76, v72
	v_add_f32_e32 v72, v72, v73
	v_max_f32_e32 v72, 0xc2a00000, v72
	v_mul_f32_e32 v72, 0xbfb8aa3b, v72
	v_exp_f32_e32 v72, v72
	ds_write_b32 v71, v69
	v_lshl_add_u32 v76, v86, 6, s0
	v_add_f32_e32 v71, 1.0, v72
	ds_read_b128 v[72:75], v76
	ds_read_b128 v[94:97], v76 offset:16
	ds_read_b128 v[98:101], v76 offset:32
	ds_read_b128 v[102:105], v76 offset:48
	v_log_f32_e32 v71, v71
	s_waitcnt lgkmcnt(3)
	v_mov_b32_e32 v76, v72
	s_waitcnt lgkmcnt(2)
	v_mov_b32_e32 v77, v94
	v_mov_b32_e32 v94, v73
	v_pk_mul_f32 v[72:73], v[54:55], v[94:95]
	v_mul_f32_e32 v71, 0x3f317218, v71
	v_pk_fma_f32 v[72:73], v[52:53], v[76:77], v[72:73]
	v_mov_b32_e32 v76, v74
	v_mov_b32_e32 v77, v96
	v_pk_fma_f32 v[72:73], v[60:61], v[76:77], v[72:73]
	v_mov_b32_e32 v96, v75
	v_pk_fma_f32 v[72:73], v[50:51], v[96:97], v[72:73]
	v_fmac_f32_e32 v69, 0xbd800000, v71
	v_add_f32_e32 v72, v85, v72
	v_add_f32_e32 v76, v72, v73
	s_waitcnt lgkmcnt(0)
	v_mov_b32_e32 v73, v102
	v_mov_b32_e32 v102, v99
	v_mov_b32_e32 v72, v98
	v_pk_mul_f32 v[74:75], v[58:59], v[102:103]
	v_lshl_add_u32 v71, v87, 10, v68
	v_pk_fma_f32 v[72:73], v[56:57], v[72:73], v[74:75]
	v_mov_b32_e32 v74, v100
	v_mov_b32_e32 v75, v104
	v_pk_fma_f32 v[72:73], v[64:65], v[74:75], v[72:73]
	v_mov_b32_e32 v104, v101
	v_pk_fma_f32 v[72:73], v[62:63], v[104:105], v[72:73]
	v_or_b32_e32 v87, 25, v70
	v_add_f32_e32 v72, v76, v72
	v_add_f32_e32 v72, v72, v73
	v_max_f32_e32 v72, 0xc2a00000, v72
	v_mul_f32_e32 v72, 0xbfb8aa3b, v72
	v_exp_f32_e32 v72, v72
	ds_write_b32 v71, v69
	v_lshl_add_u32 v76, v87, 6, s0
	v_add_f32_e32 v71, 1.0, v72
	ds_read_b128 v[72:75], v76
	ds_read_b128 v[94:97], v76 offset:16
	ds_read_b128 v[98:101], v76 offset:32
	ds_read_b128 v[102:105], v76 offset:48
	v_log_f32_e32 v71, v71
	s_waitcnt lgkmcnt(3)
	v_mov_b32_e32 v76, v72
	s_waitcnt lgkmcnt(2)
	v_mov_b32_e32 v77, v94
	v_mov_b32_e32 v94, v73
	v_pk_mul_f32 v[72:73], v[54:55], v[94:95]
	v_mul_f32_e32 v71, 0x3f317218, v71
	v_pk_fma_f32 v[72:73], v[52:53], v[76:77], v[72:73]
	v_mov_b32_e32 v76, v74
	v_mov_b32_e32 v77, v96
	v_pk_fma_f32 v[72:73], v[60:61], v[76:77], v[72:73]
	v_mov_b32_e32 v96, v75
	v_pk_fma_f32 v[72:73], v[50:51], v[96:97], v[72:73]
	v_fmac_f32_e32 v69, 0xbd800000, v71
	v_add_f32_e32 v72, v85, v72
	v_add_f32_e32 v76, v72, v73
	s_waitcnt lgkmcnt(0)
	v_mov_b32_e32 v73, v102
	v_mov_b32_e32 v102, v99
	v_mov_b32_e32 v72, v98
	v_pk_mul_f32 v[74:75], v[58:59], v[102:103]
	v_lshl_add_u32 v71, v86, 10, v68
	v_pk_fma_f32 v[72:73], v[56:57], v[72:73], v[74:75]
	v_mov_b32_e32 v74, v100
	v_mov_b32_e32 v75, v104
	v_pk_fma_f32 v[72:73], v[64:65], v[74:75], v[72:73]
	v_mov_b32_e32 v104, v101
	v_pk_fma_f32 v[72:73], v[62:63], v[104:105], v[72:73]
	v_or_b32_e32 v86, 26, v70
	v_add_f32_e32 v72, v76, v72
	v_add_f32_e32 v72, v72, v73
	v_max_f32_e32 v72, 0xc2a00000, v72
	v_mul_f32_e32 v72, 0xbfb8aa3b, v72
	v_exp_f32_e32 v72, v72
	ds_write_b32 v71, v69
	v_lshl_add_u32 v76, v86, 6, s0
	v_add_f32_e32 v71, 1.0, v72
	ds_read_b128 v[72:75], v76
	ds_read_b128 v[94:97], v76 offset:16
	ds_read_b128 v[98:101], v76 offset:32
	ds_read_b128 v[102:105], v76 offset:48
	v_log_f32_e32 v71, v71
	s_waitcnt lgkmcnt(3)
	v_mov_b32_e32 v76, v72
	s_waitcnt lgkmcnt(2)
	v_mov_b32_e32 v77, v94
	v_mov_b32_e32 v94, v73
	v_pk_mul_f32 v[72:73], v[54:55], v[94:95]
	v_mul_f32_e32 v71, 0x3f317218, v71
	v_pk_fma_f32 v[72:73], v[52:53], v[76:77], v[72:73]
	v_mov_b32_e32 v76, v74
	v_mov_b32_e32 v77, v96
	v_pk_fma_f32 v[72:73], v[60:61], v[76:77], v[72:73]
	v_mov_b32_e32 v96, v75
	v_pk_fma_f32 v[72:73], v[50:51], v[96:97], v[72:73]
	v_fmac_f32_e32 v69, 0xbd800000, v71
	v_add_f32_e32 v72, v85, v72
	v_add_f32_e32 v76, v72, v73
	s_waitcnt lgkmcnt(0)
	v_mov_b32_e32 v73, v102
	v_mov_b32_e32 v102, v99
	v_mov_b32_e32 v72, v98
	v_pk_mul_f32 v[74:75], v[58:59], v[102:103]
	v_lshl_add_u32 v71, v87, 10, v68
	v_pk_fma_f32 v[72:73], v[56:57], v[72:73], v[74:75]
	v_mov_b32_e32 v74, v100
	v_mov_b32_e32 v75, v104
	v_pk_fma_f32 v[72:73], v[64:65], v[74:75], v[72:73]
	v_mov_b32_e32 v104, v101
	v_pk_fma_f32 v[72:73], v[62:63], v[104:105], v[72:73]
	v_or_b32_e32 v87, 27, v70
	v_add_f32_e32 v72, v76, v72
	v_add_f32_e32 v72, v72, v73
	v_max_f32_e32 v72, 0xc2a00000, v72
	v_mul_f32_e32 v72, 0xbfb8aa3b, v72
	v_exp_f32_e32 v72, v72
	ds_write_b32 v71, v69
	v_lshl_add_u32 v76, v87, 6, s0
	v_add_f32_e32 v71, 1.0, v72
	ds_read_b128 v[72:75], v76
	ds_read_b128 v[94:97], v76 offset:16
	ds_read_b128 v[98:101], v76 offset:32
	ds_read_b128 v[102:105], v76 offset:48
	v_log_f32_e32 v71, v71
	s_waitcnt lgkmcnt(3)
	v_mov_b32_e32 v76, v72
	s_waitcnt lgkmcnt(2)
	v_mov_b32_e32 v77, v94
	v_mov_b32_e32 v94, v73
	v_pk_mul_f32 v[72:73], v[54:55], v[94:95]
	v_mul_f32_e32 v71, 0x3f317218, v71
	v_pk_fma_f32 v[72:73], v[52:53], v[76:77], v[72:73]
	v_mov_b32_e32 v76, v74
	v_mov_b32_e32 v77, v96
	v_pk_fma_f32 v[72:73], v[60:61], v[76:77], v[72:73]
	v_mov_b32_e32 v96, v75
	v_pk_fma_f32 v[72:73], v[50:51], v[96:97], v[72:73]
	v_fmac_f32_e32 v69, 0xbd800000, v71
	v_add_f32_e32 v72, v85, v72
	v_add_f32_e32 v76, v72, v73
	s_waitcnt lgkmcnt(0)
	v_mov_b32_e32 v73, v102
	v_mov_b32_e32 v102, v99
	v_mov_b32_e32 v72, v98
	v_pk_mul_f32 v[74:75], v[58:59], v[102:103]
	v_lshl_add_u32 v71, v86, 10, v68
	v_pk_fma_f32 v[72:73], v[56:57], v[72:73], v[74:75]
	v_mov_b32_e32 v74, v100
	v_mov_b32_e32 v75, v104
	v_pk_fma_f32 v[72:73], v[64:65], v[74:75], v[72:73]
	v_mov_b32_e32 v104, v101
	v_pk_fma_f32 v[72:73], v[62:63], v[104:105], v[72:73]
	v_or_b32_e32 v86, 28, v70
	v_add_f32_e32 v72, v76, v72
	v_add_f32_e32 v72, v72, v73
	v_max_f32_e32 v72, 0xc2a00000, v72
	v_mul_f32_e32 v72, 0xbfb8aa3b, v72
	v_exp_f32_e32 v72, v72
	ds_write_b32 v71, v69
	v_lshl_add_u32 v76, v86, 6, s0
	v_add_f32_e32 v71, 1.0, v72
	ds_read_b128 v[72:75], v76
	ds_read_b128 v[94:97], v76 offset:16
	ds_read_b128 v[98:101], v76 offset:32
	ds_read_b128 v[102:105], v76 offset:48
	v_log_f32_e32 v71, v71
	s_waitcnt lgkmcnt(3)
	v_mov_b32_e32 v76, v72
	s_waitcnt lgkmcnt(2)
	v_mov_b32_e32 v77, v94
	v_mov_b32_e32 v94, v73
	v_pk_mul_f32 v[72:73], v[54:55], v[94:95]
	v_mul_f32_e32 v71, 0x3f317218, v71
	v_pk_fma_f32 v[72:73], v[52:53], v[76:77], v[72:73]
	v_mov_b32_e32 v76, v74
	v_mov_b32_e32 v77, v96
	v_pk_fma_f32 v[72:73], v[60:61], v[76:77], v[72:73]
	v_mov_b32_e32 v96, v75
	v_pk_fma_f32 v[72:73], v[50:51], v[96:97], v[72:73]
	v_fmac_f32_e32 v69, 0xbd800000, v71
	v_add_f32_e32 v72, v85, v72
	v_add_f32_e32 v76, v72, v73
	s_waitcnt lgkmcnt(0)
	v_mov_b32_e32 v73, v102
	v_mov_b32_e32 v102, v99
	v_mov_b32_e32 v72, v98
	v_pk_mul_f32 v[74:75], v[58:59], v[102:103]
	v_lshl_add_u32 v71, v87, 10, v68
	v_pk_fma_f32 v[72:73], v[56:57], v[72:73], v[74:75]
	v_mov_b32_e32 v74, v100
	v_mov_b32_e32 v75, v104
	v_pk_fma_f32 v[72:73], v[64:65], v[74:75], v[72:73]
	v_mov_b32_e32 v104, v101
	v_pk_fma_f32 v[72:73], v[62:63], v[104:105], v[72:73]
	ds_write_b32 v71, v69
	v_add_f32_e32 v72, v76, v72
	v_add_f32_e32 v72, v72, v73
	v_max_f32_e32 v72, 0xc2a00000, v72
	v_mul_f32_e32 v72, 0xbfb8aa3b, v72
	v_exp_f32_e32 v72, v72
	v_lshl_add_u32 v76, v106, 6, s0
	v_add_f32_e32 v71, 1.0, v72
	ds_read_b128 v[72:75], v76
	ds_read_b128 v[94:97], v76 offset:16
	ds_read_b128 v[98:101], v76 offset:32
	ds_read_b128 v[102:105], v76 offset:48
	v_log_f32_e32 v71, v71
	s_waitcnt lgkmcnt(3)
	v_mov_b32_e32 v76, v72
	s_waitcnt lgkmcnt(2)
	v_mov_b32_e32 v77, v94
	v_mov_b32_e32 v94, v73
	v_pk_mul_f32 v[72:73], v[54:55], v[94:95]
	v_mul_f32_e32 v71, 0x3f317218, v71
	v_pk_fma_f32 v[72:73], v[52:53], v[76:77], v[72:73]
	v_mov_b32_e32 v76, v74
	v_mov_b32_e32 v77, v96
	v_pk_fma_f32 v[72:73], v[60:61], v[76:77], v[72:73]
	v_mov_b32_e32 v96, v75
	v_pk_fma_f32 v[72:73], v[50:51], v[96:97], v[72:73]
	v_fmac_f32_e32 v69, 0xbd800000, v71
	v_add_f32_e32 v72, v85, v72
	v_add_f32_e32 v76, v72, v73
	s_waitcnt lgkmcnt(0)
	v_mov_b32_e32 v73, v102
	v_mov_b32_e32 v102, v99
	v_mov_b32_e32 v72, v98
	v_pk_mul_f32 v[74:75], v[58:59], v[102:103]
	v_or_b32_e32 v103, 30, v70
	v_pk_fma_f32 v[72:73], v[56:57], v[72:73], v[74:75]
	v_mov_b32_e32 v74, v100
	v_mov_b32_e32 v75, v104
	v_pk_fma_f32 v[72:73], v[64:65], v[74:75], v[72:73]
	v_mov_b32_e32 v104, v101
	v_pk_fma_f32 v[72:73], v[62:63], v[104:105], v[72:73]
	v_lshl_add_u32 v87, v103, 6, s0
	v_add_f32_e32 v72, v76, v72
	v_add_f32_e32 v72, v72, v73
	v_max_f32_e32 v72, 0xc2a00000, v72
	v_mul_f32_e32 v72, 0xbfb8aa3b, v72
	v_exp_f32_e32 v72, v72
	v_lshl_add_u32 v102, v86, 10, v68
	v_add_f32_e32 v86, 1.0, v72
	ds_read_b128 v[70:73], v87
	ds_read_b128 v[74:77], v87 offset:16
	ds_read_b128 v[94:97], v87 offset:32
	ds_read_b128 v[98:101], v87 offset:48
	v_log_f32_e32 v104, v86
	ds_write_b32 v102, v69
	s_waitcnt lgkmcnt(4)
	v_mov_b32_e32 v86, v70
	s_waitcnt lgkmcnt(3)
	v_mov_b32_e32 v87, v74
	v_mov_b32_e32 v74, v71
	v_pk_mul_f32 v[70:71], v[54:55], v[74:75]
	v_mov_b32_e32 v74, v72
	v_pk_fma_f32 v[70:71], v[52:53], v[86:87], v[70:71]
	v_mov_b32_e32 v75, v76
	v_pk_fma_f32 v[70:71], v[60:61], v[74:75], v[70:71]
	v_mov_b32_e32 v76, v73
	v_pk_fma_f32 v[70:71], v[50:51], v[76:77], v[70:71]
	v_lshl_add_u32 v87, v93, 6, s0
	v_add_f32_e32 v70, v85, v70
	v_add_f32_e32 v74, v70, v71
	s_waitcnt lgkmcnt(1)
	v_mov_b32_e32 v71, v98
	v_mov_b32_e32 v98, v95
	v_mov_b32_e32 v70, v94
	v_pk_mul_f32 v[72:73], v[58:59], v[98:99]
	s_movk_i32 s0, 0x100
	v_pk_fma_f32 v[70:71], v[56:57], v[70:71], v[72:73]
	v_mov_b32_e32 v72, v96
	v_mov_b32_e32 v73, v100
	v_pk_fma_f32 v[70:71], v[64:65], v[72:73], v[70:71]
	v_mov_b32_e32 v100, v97
	v_pk_fma_f32 v[70:71], v[62:63], v[100:101], v[70:71]
	v_cmp_gt_u32_e32 vcc, s0, v0
	v_add_f32_e32 v70, v74, v70
	v_add_f32_e32 v70, v70, v71
	v_max_f32_e32 v70, 0xc2a00000, v70
	v_mul_f32_e32 v70, 0xbfb8aa3b, v70
	v_exp_f32_e32 v70, v70
	v_mul_f32_e32 v71, 0x3f317218, v104
	v_fmac_f32_e32 v69, 0xbd800000, v71
	v_add_f32_e32 v86, 1.0, v70
	ds_read_b128 v[70:73], v87
	ds_read_b128 v[74:77], v87 offset:16
	ds_read_b128 v[94:97], v87 offset:32
	ds_read_b128 v[98:101], v87 offset:48
	v_log_f32_e32 v102, v86
	s_waitcnt lgkmcnt(3)
	v_mov_b32_e32 v86, v70
	s_waitcnt lgkmcnt(2)
	v_mov_b32_e32 v87, v74
	v_mov_b32_e32 v74, v71
	v_pk_mul_f32 v[54:55], v[54:55], v[74:75]
	s_nop 0
	v_pk_fma_f32 v[52:53], v[52:53], v[86:87], v[54:55]
	v_mov_b32_e32 v54, v72
	v_mov_b32_e32 v55, v76
	v_pk_fma_f32 v[52:53], v[60:61], v[54:55], v[52:53]
	v_mov_b32_e32 v76, v73
	v_pk_fma_f32 v[50:51], v[50:51], v[76:77], v[52:53]
	s_nop 0
	v_add_f32_e32 v50, v85, v50
	v_add_f32_e32 v54, v50, v51
	s_waitcnt lgkmcnt(0)
	v_mov_b32_e32 v51, v98
	v_mov_b32_e32 v98, v95
	v_mov_b32_e32 v50, v94
	v_pk_mul_f32 v[52:53], v[58:59], v[98:99]
	s_nop 0
	v_pk_fma_f32 v[50:51], v[56:57], v[50:51], v[52:53]
	v_mov_b32_e32 v52, v96
	v_mov_b32_e32 v53, v100
	v_pk_fma_f32 v[50:51], v[64:65], v[52:53], v[50:51]
	v_mov_b32_e32 v100, v97
	v_pk_fma_f32 v[50:51], v[62:63], v[100:101], v[50:51]
	s_nop 0
	v_add_f32_e32 v50, v54, v50
	v_add_f32_e32 v50, v50, v51
	v_max_f32_e32 v50, 0xc2a00000, v50
	v_mul_f32_e32 v50, 0xbfb8aa3b, v50
	v_exp_f32_e32 v50, v50
	v_lshl_add_u32 v51, v106, 10, v68
	ds_write_b32 v51, v69
	v_mul_f32_e32 v51, 0x3f317218, v102
	v_add_f32_e32 v50, 1.0, v50
	v_log_f32_e32 v50, v50
	v_fmac_f32_e32 v69, 0xbd800000, v51
	v_lshl_add_u32 v51, v103, 10, v68
	ds_write_b32 v51, v69
	v_mul_f32_e32 v50, 0x3f317218, v50
	v_fmac_f32_e32 v69, 0xbd800000, v50
	v_lshl_add_u32 v50, v93, 10, v68
	ds_write_b32 v50, v69
	s_and_saveexec_b64 s[0:1], vcc
	v_lshl_add_u32 v50, v84, 2, 0
	v_add_u32_e32 v50, 0x24000, v50
	ds_write_b32 v50, v69
	s_or_b64 exec, exec, s[0:1]
	v_and_b32_e32 v68, 31, v0
	v_lshl_add_u32 v84, v68, 5, 0
	v_add_u32_e32 v62, 0x24000, v84
	s_add_i32 s2, 0, 0x1a000
	v_lshl_add_u32 v86, v92, 10, v84
	s_waitcnt lgkmcnt(0)
	s_barrier
	ds_read_b128 v[54:57], v84 offset:64512
	ds_read_b128 v[50:53], v84 offset:64528
	ds_read_b128 v[58:61], v62
	ds_read_b128 v[62:65], v62 offset:16
	v_lshl_add_u32 v85, v68, 4, s2
	ds_read_b128 v[68:71], v86
	s_movk_i32 s0, 0x240
	s_waitcnt lgkmcnt(2)
	v_pk_add_f32 v[76:77], v[54:55], v[58:59]
	s_waitcnt lgkmcnt(1)
	v_pk_add_f32 v[72:73], v[52:53], v[64:65]
	v_pk_add_f32 v[74:75], v[50:51], v[62:63]
	ds_read_b128 v[62:65], v86 offset:16
	s_waitcnt lgkmcnt(1)
	v_sub_f32_e32 v58, v76, v68
	v_sub_f32_e32 v59, v77, v69
	v_mul_f32_e32 v58, 0x3fb8aa3b, v58
	v_mul_f32_e32 v59, 0x3fb8aa3b, v59
	v_exp_f32_e32 v58, v58
	v_exp_f32_e32 v59, v59
	v_pk_add_f32 v[68:69], v[56:57], v[60:61]
	v_lshlrev_b32_e32 v60, 16, v14
	v_and_b32_e32 v61, 0xffff0000, v14
	v_sub_f32_e32 v14, v68, v70
	v_mul_f32_e32 v14, 0x3fb8aa3b, v14
	v_pk_mul_f32 v[58:59], v[58:59], v[60:61]
	v_exp_f32_e32 v60, v14
	v_sub_f32_e32 v14, v69, v71
	v_mul_f32_e32 v14, 0x3fb8aa3b, v14
	v_exp_f32_e32 v61, v14
	v_cvt_pk_bf16_f32 v14, v58, v59
	v_lshlrev_b32_e32 v58, 16, v15
	v_and_b32_e32 v59, 0xffff0000, v15
	s_waitcnt lgkmcnt(0)
	v_sub_f32_e32 v15, v74, v62
	v_mul_f32_e32 v15, 0x3fb8aa3b, v15
	v_pk_mul_f32 v[58:59], v[60:61], v[58:59]
	v_exp_f32_e32 v60, v15
	v_sub_f32_e32 v15, v75, v63
	v_mul_f32_e32 v15, 0x3fb8aa3b, v15
	v_exp_f32_e32 v61, v15
	v_cvt_pk_bf16_f32 v15, v58, v59
	v_lshlrev_b32_e32 v58, 16, v16
	v_and_b32_e32 v59, 0xffff0000, v16
	v_sub_f32_e32 v16, v72, v64
	v_mul_f32_e32 v16, 0x3fb8aa3b, v16
	v_pk_mul_f32 v[58:59], v[60:61], v[58:59]
	v_exp_f32_e32 v60, v16
	v_sub_f32_e32 v16, v73, v65
	v_mul_f32_e32 v16, 0x3fb8aa3b, v16
	v_exp_f32_e32 v61, v16
	v_cvt_pk_bf16_f32 v16, v58, v59
	v_lshlrev_b32_e32 v58, 16, v17
	v_and_b32_e32 v59, 0xffff0000, v17
	v_lshl_add_u32 v64, v91, 10, v84
	v_pk_mul_f32 v[62:63], v[60:61], v[58:59]
	ds_read_b128 v[58:61], v64
	v_cvt_pk_bf16_f32 v17, v62, v63
	v_mad_u32_u24 v70, v92, s0, v85
	ds_write_b128 v70, v[14:17]
	v_lshlrev_b32_e32 v14, 16, v10
	s_waitcnt lgkmcnt(1)
	v_sub_f32_e32 v58, v76, v58
	v_sub_f32_e32 v59, v77, v59
	v_mul_f32_e32 v58, 0x3fb8aa3b, v58
	v_mul_f32_e32 v59, 0x3fb8aa3b, v59
	v_and_b32_e32 v15, 0xffff0000, v10
	v_sub_f32_e32 v10, v68, v60
	ds_read_b128 v[62:65], v64 offset:16
	v_exp_f32_e32 v58, v58
	v_exp_f32_e32 v59, v59
	v_mul_f32_e32 v10, 0x3fb8aa3b, v10
	v_exp_f32_e32 v16, v10
	v_sub_f32_e32 v10, v69, v61
	v_mul_f32_e32 v10, 0x3fb8aa3b, v10
	v_exp_f32_e32 v17, v10
	v_pk_mul_f32 v[14:15], v[58:59], v[14:15]
	v_lshlrev_b32_e32 v60, 16, v13
	v_cvt_pk_bf16_f32 v10, v14, v15
	v_lshlrev_b32_e32 v14, 16, v11
	v_and_b32_e32 v15, 0xffff0000, v11
	s_waitcnt lgkmcnt(0)
	v_sub_f32_e32 v11, v74, v62
	v_mul_f32_e32 v11, 0x3fb8aa3b, v11
	v_pk_mul_f32 v[14:15], v[16:17], v[14:15]
	v_exp_f32_e32 v16, v11
	v_sub_f32_e32 v11, v75, v63
	v_mul_f32_e32 v11, 0x3fb8aa3b, v11
	v_exp_f32_e32 v17, v11
	v_cvt_pk_bf16_f32 v11, v14, v15
	v_lshlrev_b32_e32 v14, 16, v12
	v_and_b32_e32 v15, 0xffff0000, v12
	v_pk_mul_f32 v[14:15], v[16:17], v[14:15]
	v_lshl_add_u32 v62, v90, 10, v84
	v_cvt_pk_bf16_f32 v12, v14, v15
	v_sub_f32_e32 v14, v72, v64
	v_mul_f32_e32 v14, 0x3fb8aa3b, v14
	v_exp_f32_e32 v58, v14
	v_sub_f32_e32 v14, v73, v65
	v_mul_f32_e32 v14, 0x3fb8aa3b, v14
	v_exp_f32_e32 v59, v14
	ds_read_b128 v[14:17], v62
	v_and_b32_e32 v61, 0xffff0000, v13
	v_mad_u32_u24 v63, v91, s0, v85
	v_pk_mul_f32 v[58:59], v[58:59], v[60:61]
	s_nop 0
	v_cvt_pk_bf16_f32 v13, v58, v59
	ds_read_b128 v[58:61], v62 offset:16
	s_waitcnt lgkmcnt(1)
	v_sub_f32_e32 v14, v54, v14
	v_sub_f32_e32 v15, v55, v15
	v_mul_f32_e32 v14, 0x3fb8aa3b, v14
	v_mul_f32_e32 v15, 0x3fb8aa3b, v15
	ds_write_b128 v63, v[10:13]
	v_lshlrev_b32_e32 v10, 16, v6
	v_and_b32_e32 v11, 0xffff0000, v6
	v_sub_f32_e32 v6, v56, v16
	v_exp_f32_e32 v14, v14
	v_exp_f32_e32 v15, v15
	v_mul_f32_e32 v6, 0x3fb8aa3b, v6
	v_exp_f32_e32 v12, v6
	v_sub_f32_e32 v6, v57, v17
	v_mul_f32_e32 v6, 0x3fb8aa3b, v6
	v_exp_f32_e32 v13, v6
	v_pk_mul_f32 v[10:11], v[14:15], v[10:11]
	v_lshlrev_b32_e32 v14, 16, v2
	v_cvt_pk_bf16_f32 v6, v10, v11
	v_lshlrev_b32_e32 v10, 16, v7
	v_and_b32_e32 v11, 0xffff0000, v7
	s_waitcnt lgkmcnt(1)
	v_sub_f32_e32 v7, v50, v58
	v_mul_f32_e32 v7, 0x3fb8aa3b, v7
	v_pk_mul_f32 v[10:11], v[12:13], v[10:11]
	v_exp_f32_e32 v12, v7
	v_sub_f32_e32 v7, v51, v59
	v_mul_f32_e32 v7, 0x3fb8aa3b, v7
	v_exp_f32_e32 v13, v7
	v_cvt_pk_bf16_f32 v7, v10, v11
	v_lshlrev_b32_e32 v10, 16, v8
	v_and_b32_e32 v11, 0xffff0000, v8
	v_sub_f32_e32 v8, v52, v60
	v_mul_f32_e32 v8, 0x3fb8aa3b, v8
	v_pk_mul_f32 v[10:11], v[12:13], v[10:11]
	v_exp_f32_e32 v12, v8
	v_sub_f32_e32 v8, v53, v61
	v_mul_f32_e32 v8, 0x3fb8aa3b, v8
	v_exp_f32_e32 v13, v8
	v_cvt_pk_bf16_f32 v8, v10, v11
	v_lshlrev_b32_e32 v10, 16, v9
	v_and_b32_e32 v11, 0xffff0000, v9
	v_pk_mul_f32 v[10:11], v[12:13], v[10:11]
	v_and_b32_e32 v15, 0xffff0000, v2
	v_cvt_pk_bf16_f32 v9, v10, v11
	v_mad_u32_u24 v10, v90, s0, v85
	ds_write_b128 v10, v[6:9]
	v_lshl_add_u32 v10, v89, 10, v84
	ds_read_b128 v[6:9], v10
	ds_read_b128 v[10:13], v10 offset:16
	s_waitcnt lgkmcnt(1)
	v_sub_f32_e32 v6, v54, v6
	v_sub_f32_e32 v7, v55, v7
	v_mul_f32_e32 v6, 0x3fb8aa3b, v6
	v_mul_f32_e32 v7, 0x3fb8aa3b, v7
	v_sub_f32_e32 v2, v56, v8
	v_exp_f32_e32 v6, v6
	v_exp_f32_e32 v7, v7
	v_mul_f32_e32 v2, 0x3fb8aa3b, v2
	v_exp_f32_e32 v8, v2
	v_sub_f32_e32 v2, v57, v9
	v_mul_f32_e32 v2, 0x3fb8aa3b, v2
	v_exp_f32_e32 v9, v2
	v_pk_mul_f32 v[6:7], v[6:7], v[14:15]
	s_nop 0
	v_cvt_pk_bf16_f32 v2, v6, v7
	v_lshlrev_b32_e32 v6, 16, v3
	v_and_b32_e32 v7, 0xffff0000, v3
	s_waitcnt lgkmcnt(0)
	v_sub_f32_e32 v3, v50, v10
	v_mul_f32_e32 v3, 0x3fb8aa3b, v3
	v_pk_mul_f32 v[6:7], v[8:9], v[6:7]
	v_exp_f32_e32 v8, v3
	v_sub_f32_e32 v3, v51, v11
	v_mul_f32_e32 v3, 0x3fb8aa3b, v3
	v_exp_f32_e32 v9, v3
	v_cvt_pk_bf16_f32 v3, v6, v7
	v_lshlrev_b32_e32 v6, 16, v4
	v_and_b32_e32 v7, 0xffff0000, v4
	v_sub_f32_e32 v4, v52, v12
	v_mul_f32_e32 v4, 0x3fb8aa3b, v4
	v_pk_mul_f32 v[6:7], v[8:9], v[6:7]
	v_exp_f32_e32 v8, v4
	v_sub_f32_e32 v4, v53, v13
	v_mul_f32_e32 v4, 0x3fb8aa3b, v4
	v_exp_f32_e32 v9, v4
	v_cvt_pk_bf16_f32 v4, v6, v7
	v_lshlrev_b32_e32 v6, 16, v5
	v_and_b32_e32 v7, 0xffff0000, v5
	v_pk_mul_f32 v[6:7], v[8:9], v[6:7]
	s_nop 0
	v_cvt_pk_bf16_f32 v5, v6, v7
	v_mad_u32_u24 v6, v89, s0, v85
	ds_write_b128 v6, v[2:5]
	s_and_saveexec_b64 s[0:1], vcc
	s_cbranch_execz .LBB0_389
	v_lshl_add_u32 v2, v0, 2, 0
	v_add_u32_e32 v3, 0x24000, v2
	ds_read_b32 v4, v2 offset:64512
	ds_read_b32 v5, v3
	v_lshl_or_b32 v2, s6, 8, v0
	v_ashrrev_i32_e32 v3, 31, v2
	v_lshl_add_u64 v[2:3], v[2:3], 2, s[58:59]
	v_add_co_u32_e32 v2, vcc, 0x180000, v2
	s_waitcnt lgkmcnt(0)
	v_add_f32_e32 v4, v4, v5
	v_mul_f32_e32 v4, 0x3fb8aa3b, v4
	v_exp_f32_e32 v4, v4
	v_addc_co_u32_e32 v3, vcc, 0, v3, vcc
	global_store_dword v[2:3], v4, off

	.amdhsa_kernel _Z6mk_fwd4Args
		.amdhsa_group_segment_fixed_size 0
		.amdhsa_private_segment_fixed_size 0
		.amdhsa_kernarg_size 424
		.amdhsa_user_sgpr_count 2
		.amdhsa_user_sgpr_dispatch_ptr 0
		.amdhsa_user_sgpr_queue_ptr 0
		.amdhsa_user_sgpr_kernarg_segment_ptr 1
		.amdhsa_user_sgpr_dispatch_id 0
		.amdhsa_user_sgpr_kernarg_preload_length 0
		.amdhsa_user_sgpr_kernarg_preload_offset 0
		.amdhsa_user_sgpr_private_segment_size 0
		.amdhsa_uses_dynamic_stack 0
		.amdhsa_enable_private_segment 0
		.amdhsa_system_sgpr_workgroup_id_x 1
		.amdhsa_system_sgpr_workgroup_id_y 0
		.amdhsa_system_sgpr_workgroup_id_z 0
		.amdhsa_system_sgpr_workgroup_info 0
		.amdhsa_system_vgpr_workitem_id 0
		.amdhsa_next_free_vgpr 255
		.amdhsa_next_free_sgpr 102
		.amdhsa_accum_offset 256
		.amdhsa_reserve_vcc 1
		.amdhsa_float_round_mode_32 0
		.amdhsa_float_round_mode_16_64 0
		.amdhsa_float_denorm_mode_32 3
		.amdhsa_float_denorm_mode_16_64 3
		.amdhsa_dx10_clamp 1
		.amdhsa_ieee_mode 1
		.amdhsa_fp16_overflow 0
		.amdhsa_tg_split 0
		.amdhsa_exception_fp_ieee_invalid_op 0
		.amdhsa_exception_fp_denorm_src 0
		.amdhsa_exception_fp_ieee_div_zero 0
		.amdhsa_exception_fp_ieee_overflow 0
		.amdhsa_exception_fp_ieee_underflow 0
		.amdhsa_exception_fp_ieee_inexact 0
		.amdhsa_exception_int_div_zero 0
	.end_amdhsa_kernel

amdhsa.kernels:
  - .agpr_count:     0
    .args:
      - .offset:         0
        .size:           168
        .value_kind:     by_value
      - .offset:         168
        .size:           4
        .value_kind:     hidden_block_count_x
      - .offset:         172
        .size:           4
        .value_kind:     hidden_block_count_y
      - .offset:         176
        .size:           4
        .value_kind:     hidden_block_count_z
      - .offset:         180
        .size:           2
        .value_kind:     hidden_group_size_x
      - .offset:         182
        .size:           2
        .value_kind:     hidden_group_size_y
      - .offset:         184
        .size:           2
        .value_kind:     hidden_group_size_z
      - .offset:         186
        .size:           2
        .value_kind:     hidden_remainder_x
      - .offset:         188
        .size:           2
        .value_kind:     hidden_remainder_y
      - .offset:         190
        .size:           2
        .value_kind:     hidden_remainder_z
      - .offset:         208
        .size:           8
        .value_kind:     hidden_global_offset_x
      - .offset:         216
        .size:           8
        .value_kind:     hidden_global_offset_y
      - .offset:         224
        .size:           8
        .value_kind:     hidden_global_offset_z
      - .offset:         232
        .size:           2
        .value_kind:     hidden_grid_dims
      - .offset:         288
        .size:           4
        .value_kind:     hidden_dynamic_lds_size
    .group_segment_fixed_size: 0
    .kernarg_segment_align: 8
    .kernarg_segment_size: 424
    .language:       OpenCL C
    .language_version:
      - 2
      - 0
    .max_flat_workgroup_size: 512
    .name:           _Z6mk_fwd4Args
    .private_segment_fixed_size: 0
    .sgpr_count:     108
    .sgpr_spill_count: 31
    .symbol:         _Z6mk_fwd4Args.kd
    .uniform_work_group_size: 1
    .uses_dynamic_stack: false
    .vgpr_count:     255
    .vgpr_spill_count: 0
    .wavefront_size: 64
